# v80 + 224 (was 203) bit-trick->v_cvt_pk_bf16_f32 sites, all 10 row-phase wave reductions on DPP/permlane-swap, redundant lgkmcnt waits of the removed bpermute chains dropped
# baseline (speedup 1.0000x reference)
.LBB0_114:
	s_add_i32 s24, s20, 0xffffe001
	s_cmpk_lt_i32 s14, 0x2000
	s_cselect_b32 s25, s15, 0
	s_cselect_b32 s24, s14, s24
	s_cselect_b32 s26, s1, s3
	s_cselect_b32 s27, s0, s2
	s_lshl_b64 s[24:25], s[24:25], 13
	s_add_u32 s24, s27, s24
	s_addc_u32 s25, s26, s25
	v_lshl_add_u64 v[40:41], s[24:25], 0, v[64:65]
	v_add_co_u32_e32 v100, vcc, s19, v40
	global_load_dwordx4 v[52:55], v64, s[24:25]
	global_load_dwordx4 v[44:47], v64, s[24:25] offset:1024
	global_load_dwordx4 v[36:39], v64, s[24:25] offset:2048
	global_load_dwordx4 v[32:35], v64, s[24:25] offset:3072
	v_addc_co_u32_e32 v101, vcc, 0, v41, vcc
	global_load_dwordx4 v[60:63], v[100:101], off
	global_load_dwordx4 v[56:59], v[100:101], off offset:1024
	global_load_dwordx4 v[48:51], v[100:101], off offset:2048
	global_load_dwordx4 v[40:43], v[100:101], off offset:3072
	s_waitcnt vmcnt(7)
	v_mov_b32_e32 v104, v53
	s_waitcnt vmcnt(6)
	v_mov_b32_e32 v105, v45
	v_mov_b32_e32 v108, v55
	v_mov_b32_e32 v109, v47
	v_mov_b32_e32 v100, v52
	v_mov_b32_e32 v101, v44
	v_mov_b32_e32 v102, v54
	v_mov_b32_e32 v103, v46
	s_waitcnt vmcnt(5)
	v_pk_mul_f32 v[110:111], v[38:39], v[38:39]
	v_pk_mul_f32 v[106:107], v[36:37], v[36:37]
	v_pk_mul_f32 v[104:105], v[104:105], v[104:105]
	v_pk_mul_f32 v[108:109], v[108:109], v[108:109]
	v_pk_mov_b32 v[130:131], v[106:107], v[110:111] op_sel:[1,0]
	v_mov_b32_e32 v107, v111
	v_pk_fma_f32 v[100:101], v[100:101], v[100:101], v[104:105]
	v_pk_fma_f32 v[102:103], v[102:103], v[102:103], v[108:109]
	s_waitcnt vmcnt(4)
	v_mul_f32_e32 v112, v33, v33
	v_mul_f32_e32 v114, v35, v35
	v_pk_add_f32 v[104:105], v[130:131], v[106:107]
	v_pk_add_f32 v[100:101], v[100:101], v[102:103]
	s_waitcnt vmcnt(3)
	v_mul_f32_e32 v128, v60, v60
	v_mul_f32_e32 v129, v61, v61
	v_mul_f32_e32 v138, v62, v62
	v_mul_f32_e32 v139, v63, v63
	v_pk_fma_f32 v[110:111], v[32:33], v[32:33], v[112:113] op_sel_hi:[1,1,0]
	v_pk_fma_f32 v[132:133], v[34:35], v[34:35], v[114:115] op_sel_hi:[1,1,0]
	v_pk_add_f32 v[102:103], v[104:105], v[104:105] op_sel:[0,1] op_sel_hi:[1,0]
	v_pk_add_f32 v[100:101], v[100:101], v[100:101] op_sel:[0,1] op_sel_hi:[1,0]
	s_waitcnt vmcnt(2)
	v_pk_mul_f32 v[118:119], v[58:59], v[58:59]
	v_pk_mul_f32 v[116:117], v[56:57], v[56:57]
	v_mov_b32_e32 v111, v138
	v_mov_b32_e32 v133, v139
	v_mov_b32_e32 v103, v129
	v_mov_b32_e32 v101, v128
	v_pk_mov_b32 v[134:135], v[116:117], v[118:119] op_sel:[1,0]
	v_mov_b32_e32 v117, v119
	v_pk_add_f32 v[104:105], v[110:111], v[132:133]
	v_pk_add_f32 v[100:101], v[100:101], v[102:103]
	s_waitcnt vmcnt(1)
	v_mul_f32_e32 v120, v49, v49
	v_mul_f32_e32 v122, v51, v51
	v_pk_add_f32 v[106:107], v[134:135], v[116:117]
	v_pk_add_f32 v[100:101], v[100:101], v[104:105]
	s_waitcnt vmcnt(0)
	v_mul_f32_e32 v140, v40, v40
	v_mul_f32_e32 v141, v41, v41
	v_mul_f32_e32 v142, v42, v42
	v_mul_f32_e32 v143, v43, v43
	v_pk_fma_f32 v[118:119], v[48:49], v[48:49], v[120:121] op_sel_hi:[1,1,0]
	v_pk_fma_f32 v[136:137], v[50:51], v[50:51], v[122:123] op_sel_hi:[1,1,0]
	v_pk_add_f32 v[106:107], v[106:107], v[106:107] op_sel:[0,1] op_sel_hi:[1,0]
	v_pk_add_f32 v[100:101], v[100:101], v[100:101] op_sel:[0,1] op_sel_hi:[1,0]
	v_mov_b32_e32 v119, v142
	v_mov_b32_e32 v137, v143
	v_mov_b32_e32 v107, v141
	v_mov_b32_e32 v101, v140
	v_pk_add_f32 v[108:109], v[118:119], v[136:137]
	v_pk_add_f32 v[100:101], v[100:101], v[106:107]
	s_add_i32 s20, s20, 1
	v_pk_add_f32 v[100:101], v[100:101], v[108:109]
	s_add_u32 s14, s14, 1
	v_add_f32_e32 v100, v100, v101
	s_addc_u32 s15, s15, 0
	s_cmp_ge_i32 s20, s18
	s_waitcnt lgkmcnt(0)
	s_nop 1
	v_add_f32_dpp v100, v100, v100 quad_perm:[1,0,3,2] row_mask:0xf bank_mask:0xf
	s_nop 1
	v_add_f32_dpp v100, v100, v100 quad_perm:[2,3,0,1] row_mask:0xf bank_mask:0xf
	s_nop 1
	v_add_f32_dpp v100, v100, v100 row_half_mirror row_mask:0xf bank_mask:0xf
	s_nop 1
	v_add_f32_dpp v100, v100, v100 row_mirror row_mask:0xf bank_mask:0xf
	v_mov_b32_e32 v101, v100
	s_nop 1
	v_permlane16_swap_b32_e32 v100, v101
	v_add_f32_e32 v100, v100, v101
	v_mov_b32_e32 v101, v100
	s_nop 1
	v_permlane32_swap_b32_e32 v100, v101
	v_add_f32_e32 v100, v100, v101
	v_fmamk_f32 v100, v100, 0x3a000000, v127
	v_mul_f32_e32 v101, 0x4b800000, v100
	v_cmp_gt_f32_e32 vcc, s21, v100
	s_nop 1
	v_cndmask_b32_e32 v100, v100, v101, vcc
	v_rsq_f32_e32 v100, v100
	s_nop 0
	v_mul_f32_e32 v101, 0x45800000, v100
	v_cndmask_b32_e32 v100, v100, v101, vcc
	v_pk_mul_f32 v[52:53], v[52:53], v[100:101] op_sel_hi:[1,0]
	v_pk_mul_f32 v[54:55], v[54:55], v[100:101] op_sel_hi:[1,0]
	v_pk_mul_f32 v[44:45], v[44:45], v[100:101] op_sel_hi:[1,0]
	v_pk_mul_f32 v[46:47], v[46:47], v[100:101] op_sel_hi:[1,0]
	v_pk_mul_f32 v[36:37], v[36:37], v[100:101] op_sel_hi:[1,0]
	v_pk_mul_f32 v[38:39], v[38:39], v[100:101] op_sel_hi:[1,0]
	v_pk_mul_f32 v[32:33], v[32:33], v[100:101] op_sel_hi:[1,0]
	v_pk_mul_f32 v[34:35], v[34:35], v[100:101] op_sel_hi:[1,0]
	v_pk_mul_f32 v[60:61], v[60:61], v[100:101] op_sel_hi:[1,0]
	v_pk_mul_f32 v[62:63], v[62:63], v[100:101] op_sel_hi:[1,0]
	v_pk_mul_f32 v[56:57], v[56:57], v[100:101] op_sel_hi:[1,0]
	v_pk_mul_f32 v[58:59], v[58:59], v[100:101] op_sel_hi:[1,0]
	v_pk_mul_f32 v[48:49], v[48:49], v[100:101] op_sel_hi:[1,0]
	v_pk_mul_f32 v[50:51], v[50:51], v[100:101] op_sel_hi:[1,0]
	v_pk_mul_f32 v[40:41], v[40:41], v[100:101] op_sel_hi:[1,0]
	v_pk_mul_f32 v[42:43], v[42:43], v[100:101] op_sel_hi:[1,0]
	v_pk_fma_f32 v[54:55], v[66:67], v[54:55], v[2:3]
	v_pk_fma_f32 v[52:53], v[68:69], v[52:53], v[0:1]
	v_pk_fma_f32 v[46:47], v[70:71], v[46:47], v[6:7]
	v_pk_fma_f32 v[44:45], v[72:73], v[44:45], v[4:5]
	v_pk_fma_f32 v[38:39], v[74:75], v[38:39], v[10:11]
	v_pk_fma_f32 v[36:37], v[76:77], v[36:37], v[8:9]
	v_pk_fma_f32 v[34:35], v[78:79], v[34:35], v[14:15]
	v_pk_fma_f32 v[32:33], v[80:81], v[32:33], v[12:13]
	v_pk_fma_f32 v[62:63], v[82:83], v[62:63], v[18:19]
	v_pk_fma_f32 v[60:61], v[84:85], v[60:61], v[16:17]
	v_pk_fma_f32 v[58:59], v[86:87], v[58:59], v[22:23]
	v_pk_fma_f32 v[56:57], v[88:89], v[56:57], v[20:21]
	v_pk_fma_f32 v[50:51], v[90:91], v[50:51], v[26:27]
	v_pk_fma_f32 v[48:49], v[92:93], v[48:49], v[24:25]
	v_pk_fma_f32 v[42:43], v[94:95], v[42:43], v[30:31]
	v_pk_fma_f32 v[40:41], v[96:97], v[40:41], v[28:29]
	v_bfe_u32 v100, v52, 16, 1
	v_bfe_u32 v102, v54, 16, 1
	v_bfe_u32 v101, v53, 16, 1
	v_bfe_u32 v103, v55, 16, 1
	v_bfe_u32 v104, v44, 16, 1
	v_bfe_u32 v106, v46, 16, 1
	v_bfe_u32 v108, v36, 16, 1
	v_bfe_u32 v110, v38, 16, 1
	v_bfe_u32 v112, v32, 16, 1
	v_bfe_u32 v114, v33, 16, 1
	v_bfe_u32 v116, v34, 16, 1
	v_bfe_u32 v117, v35, 16, 1
	v_bfe_u32 v118, v60, 16, 1
	v_bfe_u32 v119, v61, 16, 1
	v_bfe_u32 v120, v62, 16, 1
	v_bfe_u32 v122, v63, 16, 1
	v_bfe_u32 v128, v56, 16, 1
	v_bfe_u32 v130, v58, 16, 1
	v_bfe_u32 v132, v48, 16, 1
	v_bfe_u32 v134, v50, 16, 1
	v_bfe_u32 v136, v40, 16, 1
	v_bfe_u32 v137, v41, 16, 1
	v_bfe_u32 v138, v42, 16, 1
	v_bfe_u32 v139, v43, 16, 1
	v_add3_u32 v52, v52, v100, s22
	v_add3_u32 v54, v54, v102, s22
	v_bfe_u32 v105, v45, 16, 1
	v_bfe_u32 v107, v47, 16, 1
	v_bfe_u32 v109, v37, 16, 1
	v_bfe_u32 v111, v39, 16, 1
	v_bfe_u32 v129, v57, 16, 1
	v_bfe_u32 v131, v59, 16, 1
	v_bfe_u32 v133, v49, 16, 1
	v_bfe_u32 v135, v51, 16, 1
	v_add3_u32 v53, v53, v101, s22
	v_add3_u32 v55, v55, v103, s22
	v_add3_u32 v44, v44, v104, s22
	v_add3_u32 v46, v46, v106, s22
	v_add3_u32 v36, v36, v108, s22
	v_add3_u32 v38, v38, v110, s22
	v_add3_u32 v32, v32, v112, s22
	v_add3_u32 v100, v33, v114, s22
	v_add3_u32 v33, v34, v116, s22
	v_add3_u32 v101, v35, v117, s22
	v_add3_u32 v34, v60, v118, s22
	v_add3_u32 v60, v61, v119, s22
	v_add3_u32 v35, v62, v120, s22
	v_add3_u32 v61, v63, v122, s22
	v_add3_u32 v56, v56, v128, s22
	v_add3_u32 v58, v58, v130, s22
	v_add3_u32 v48, v48, v132, s22
	v_add3_u32 v50, v50, v134, s22
	v_add3_u32 v40, v40, v136, s22
	v_add3_u32 v62, v41, v137, s22
	v_add3_u32 v41, v42, v138, s22
	v_add3_u32 v63, v43, v139, s22
	v_lshrrev_b32_e32 v42, 16, v52
	v_lshrrev_b32_e32 v43, 16, v54
	v_add3_u32 v45, v45, v105, s22
	v_add3_u32 v47, v47, v107, s22
	v_add3_u32 v37, v37, v109, s22
	v_add3_u32 v39, v39, v111, s22
	v_add3_u32 v57, v57, v129, s22
	v_add3_u32 v59, v59, v131, s22
	v_add3_u32 v49, v49, v133, s22
	v_add3_u32 v51, v51, v135, s22
	v_lshrrev_b32_e32 v44, 16, v44
	v_lshrrev_b32_e32 v46, 16, v46
	v_lshrrev_b32_e32 v36, 16, v36
	v_lshrrev_b32_e32 v38, 16, v38
	v_lshrrev_b32_e32 v52, 16, v32
	v_lshrrev_b32_e32 v54, 16, v33
	v_lshrrev_b32_e32 v102, 16, v34
	v_lshrrev_b32_e32 v103, 16, v35
	v_lshrrev_b32_e32 v56, 16, v56
	v_lshrrev_b32_e32 v58, 16, v58
	v_lshrrev_b32_e32 v48, 16, v48
	v_lshrrev_b32_e32 v50, 16, v50
	v_lshrrev_b32_e32 v104, 16, v40
	v_lshrrev_b32_e32 v105, 16, v41
	v_and_or_b32 v32, v53, s23, v42
	v_and_or_b32 v33, v55, s23, v43
	v_and_or_b32 v34, v45, s23, v44
	v_and_or_b32 v35, v47, s23, v46
	v_and_or_b32 v36, v37, s23, v36
	v_and_or_b32 v37, v39, s23, v38
	v_and_or_b32 v38, v100, s23, v52
	v_and_or_b32 v39, v101, s23, v54
	v_and_or_b32 v40, v60, s23, v102
	v_and_or_b32 v41, v61, s23, v103
	v_and_or_b32 v42, v57, s23, v56
	v_and_or_b32 v43, v59, s23, v58
	v_and_or_b32 v44, v49, s23, v48
	v_and_or_b32 v45, v51, s23, v50
	v_and_or_b32 v46, v62, s23, v104
	v_and_or_b32 v47, v63, s23, v105
	global_store_dwordx2 v[98:99], v[32:33], off offset:-3584
	global_store_dwordx2 v[98:99], v[34:35], off offset:-3072
	global_store_dwordx2 v[98:99], v[36:37], off offset:-2560
	global_store_dwordx2 v[98:99], v[38:39], off offset:-2048
	global_store_dwordx2 v[98:99], v[40:41], off offset:-1536
	global_store_dwordx2 v[98:99], v[42:43], off offset:-1024
	global_store_dwordx2 v[98:99], v[44:45], off offset:-512
	global_store_dwordx2 v[98:99], v[46:47], off
	v_lshl_add_u64 v[98:99], v[98:99], 0, s[16:17]
	s_cbranch_scc0 .LBB0_114
	s_branch .LBB0_120

.LBB0_119:
	s_add_i32 s12, s14, 0xffffe000
	s_ashr_i32 s13, s12, 12
	s_add_i32 s13, s13, 1
	s_cmpk_lt_i32 s14, 0x2000
	s_cselect_b32 s16, 0, s13
	s_cselect_b32 s13, s15, 0
	s_cselect_b32 s12, s14, s12
	s_cselect_b32 s17, s1, s3
	s_cselect_b32 s18, s0, s2
	s_lshl_b64 s[12:13], s[12:13], 13
	s_add_u32 s12, s18, s12
	s_addc_u32 s13, s17, s13
	v_lshl_add_u64 v[0:1], s[12:13], 0, v[124:125]
	v_add_co_u32_e32 v0, vcc, s8, v0
	global_load_dwordx4 v[36:39], v124, s[12:13]
	global_load_dwordx4 v[28:31], v124, s[12:13] offset:1024
	global_load_dwordx4 v[20:23], v124, s[12:13] offset:2048
	global_load_dwordx4 v[16:19], v124, s[12:13] offset:3072
	v_addc_co_u32_e32 v1, vcc, 0, v1, vcc
	global_load_dwordx4 v[44:47], v[0:1], off
	global_load_dwordx4 v[40:43], v[0:1], off offset:1024
	global_load_dwordx4 v[32:35], v[0:1], off offset:2048
	global_load_dwordx4 v[24:27], v[0:1], off offset:3072
	v_mad_i64_i32 v[64:65], s[12:13], s16, v173, v[136:137]
	v_add_co_u32_e32 v72, vcc, s8, v64
	v_mad_i64_i32 v[66:67], s[12:13], s16, v173, v[138:139]
	s_nop 0
	v_addc_co_u32_e32 v73, vcc, 0, v65, vcc
	v_add_co_u32_e32 v74, vcc, s8, v66
	global_load_dwordx4 v[48:51], v[126:127], off
	global_load_dwordx4 v[52:55], v[126:127], off offset:1024
	global_load_dwordx4 v[184:187], v[64:65], off
	global_load_dwordx4 v[120:123], v[64:65], off offset:1024
	global_load_dwordx4 v[4:7], v[66:67], off
	global_load_dwordx4 v[0:3], v[66:67], off offset:1024
	global_load_dwordx4 v[56:59], v[126:127], off offset:2048
	global_load_dwordx4 v[60:63], v[126:127], off offset:3072
	global_load_dwordx4 v[116:119], v[64:65], off offset:2048
	global_load_dwordx4 v[112:115], v[64:65], off offset:3072
	global_load_dwordx4 v[12:15], v[66:67], off offset:2048
	global_load_dwordx4 v[8:11], v[66:67], off offset:3072
	v_addc_co_u32_e32 v75, vcc, 0, v67, vcc
	global_load_dwordx4 v[80:83], v[128:129], off
	global_load_dwordx4 v[84:87], v[130:131], off
	global_load_dwordx4 v[108:111], v[72:73], off
	global_load_dwordx4 v[104:107], v[72:73], off offset:1024
	global_load_dwordx4 v[68:71], v[74:75], off
	global_load_dwordx4 v[64:67], v[74:75], off offset:1024
	global_load_dwordx4 v[88:91], v[132:133], off
	global_load_dwordx4 v[92:95], v[134:135], off
	global_load_dwordx4 v[100:103], v[72:73], off offset:2048
	global_load_dwordx4 v[96:99], v[72:73], off offset:3072
	global_load_dwordx4 v[76:79], v[74:75], off offset:2048
	s_nop 0
	global_load_dwordx4 v[72:75], v[74:75], off offset:3072
	s_waitcnt vmcnt(31)
	v_mov_b32_e32 v146, v37
	s_waitcnt vmcnt(30)
	v_mov_b32_e32 v147, v29
	v_mov_b32_e32 v148, v39
	v_mov_b32_e32 v149, v31
	v_mov_b32_e32 v142, v36
	v_mov_b32_e32 v143, v28
	v_mov_b32_e32 v144, v38
	v_mov_b32_e32 v145, v30
	s_waitcnt vmcnt(29)
	v_pk_mul_f32 v[152:153], v[22:23], v[22:23]
	v_pk_mul_f32 v[150:151], v[20:21], v[20:21]
	v_pk_mul_f32 v[146:147], v[146:147], v[146:147]
	v_pk_mul_f32 v[148:149], v[148:149], v[148:149]
	s_waitcnt vmcnt(21)
	v_pk_add_f32 v[164:165], v[184:185], 1.0 op_sel_hi:[1,0]
	v_pk_mov_b32 v[184:185], v[150:151], v[152:153] op_sel:[1,0]
	v_mov_b32_e32 v151, v153
	v_pk_fma_f32 v[142:143], v[142:143], v[142:143], v[146:147]
	v_pk_fma_f32 v[144:145], v[144:145], v[144:145], v[148:149]
	v_mul_f32_e32 v154, v17, v17
	v_mul_f32_e32 v156, v19, v19
	v_pk_add_f32 v[146:147], v[184:185], v[150:151]
	v_pk_add_f32 v[142:143], v[142:143], v[144:145]
	v_mul_f32_e32 v175, v44, v44
	v_mul_f32_e32 v177, v45, v45
	v_mul_f32_e32 v178, v46, v46
	v_mul_f32_e32 v179, v47, v47
	v_pk_add_f32 v[162:163], v[186:187], 1.0 op_sel_hi:[1,0]
	v_pk_fma_f32 v[152:153], v[16:17], v[16:17], v[154:155] op_sel_hi:[1,1,0]
	v_pk_fma_f32 v[186:187], v[18:19], v[18:19], v[156:157] op_sel_hi:[1,1,0]
	v_pk_add_f32 v[144:145], v[146:147], v[146:147] op_sel:[0,1] op_sel_hi:[1,0]
	v_pk_add_f32 v[142:143], v[142:143], v[142:143] op_sel:[0,1] op_sel_hi:[1,0]
	v_pk_mul_f32 v[160:161], v[42:43], v[42:43]
	v_pk_mul_f32 v[158:159], v[40:41], v[40:41]
	v_mov_b32_e32 v153, v178
	v_mov_b32_e32 v187, v179
	v_mov_b32_e32 v145, v177
	v_mov_b32_e32 v143, v175
	v_pk_mov_b32 v[188:189], v[158:159], v[160:161] op_sel:[1,0]
	v_mov_b32_e32 v159, v161
	v_pk_add_f32 v[146:147], v[152:153], v[186:187]
	v_pk_add_f32 v[142:143], v[142:143], v[144:145]
	v_mul_f32_e32 v166, v33, v33
	v_mul_f32_e32 v168, v35, v35
	v_pk_add_f32 v[148:149], v[188:189], v[158:159]
	v_pk_add_f32 v[142:143], v[142:143], v[146:147]
	v_mul_f32_e32 v180, v24, v24
	v_mul_f32_e32 v181, v25, v25
	v_mul_f32_e32 v182, v26, v26
	v_mul_f32_e32 v183, v27, v27
	v_pk_fma_f32 v[160:161], v[32:33], v[32:33], v[166:167] op_sel_hi:[1,1,0]
	v_pk_fma_f32 v[190:191], v[34:35], v[34:35], v[168:169] op_sel_hi:[1,1,0]
	v_pk_add_f32 v[148:149], v[148:149], v[148:149] op_sel:[0,1] op_sel_hi:[1,0]
	v_pk_add_f32 v[142:143], v[142:143], v[142:143] op_sel:[0,1] op_sel_hi:[1,0]
	v_mov_b32_e32 v161, v182
	v_mov_b32_e32 v191, v183
	v_mov_b32_e32 v149, v181
	v_mov_b32_e32 v143, v180
	v_pk_add_f32 v[150:151], v[160:161], v[190:191]
	v_pk_add_f32 v[142:143], v[142:143], v[148:149]
	s_waitcnt vmcnt(20)
	v_pk_add_f32 v[122:123], v[122:123], 1.0 op_sel_hi:[1,0]
	v_pk_add_f32 v[142:143], v[142:143], v[150:151]
	v_pk_add_f32 v[120:121], v[120:121], 1.0 op_sel_hi:[1,0]
	v_add_f32_e32 v142, v142, v143
	s_waitcnt vmcnt(15)
	v_pk_add_f32 v[118:119], v[118:119], 1.0 op_sel_hi:[1,0]
	v_pk_add_f32 v[116:117], v[116:117], 1.0 op_sel_hi:[1,0]
	s_waitcnt vmcnt(14)
	v_pk_add_f32 v[114:115], v[114:115], 1.0 op_sel_hi:[1,0]
	v_pk_add_f32 v[112:113], v[112:113], 1.0 op_sel_hi:[1,0]
	s_waitcnt lgkmcnt(0)
	s_waitcnt vmcnt(9)
	v_pk_add_f32 v[110:111], v[110:111], 1.0 op_sel_hi:[1,0]
	v_pk_add_f32 v[108:109], v[108:109], 1.0 op_sel_hi:[1,0]
	s_waitcnt vmcnt(8)
	v_pk_add_f32 v[106:107], v[106:107], 1.0 op_sel_hi:[1,0]
	v_pk_add_f32 v[104:105], v[104:105], 1.0 op_sel_hi:[1,0]
	s_waitcnt vmcnt(3)
	v_pk_add_f32 v[102:103], v[102:103], 1.0 op_sel_hi:[1,0]
	v_pk_add_f32 v[100:101], v[100:101], 1.0 op_sel_hi:[1,0]
	s_waitcnt vmcnt(2)
	v_pk_add_f32 v[98:99], v[98:99], 1.0 op_sel_hi:[1,0]
	v_pk_add_f32 v[96:97], v[96:97], 1.0 op_sel_hi:[1,0]
	s_add_u32 s14, s14, s50
	s_addc_u32 s15, s15, s51
	s_cmpk_gt_i32 s14, 0x3fff
	s_nop 1
	v_add_f32_dpp v142, v142, v142 quad_perm:[1,0,3,2] row_mask:0xf bank_mask:0xf
	s_nop 1
	v_add_f32_dpp v142, v142, v142 quad_perm:[2,3,0,1] row_mask:0xf bank_mask:0xf
	s_nop 1
	v_add_f32_dpp v142, v142, v142 row_half_mirror row_mask:0xf bank_mask:0xf
	s_nop 1
	v_add_f32_dpp v142, v142, v142 row_mirror row_mask:0xf bank_mask:0xf
	v_mov_b32_e32 v143, v142
	s_nop 1
	v_permlane16_swap_b32_e32 v142, v143
	v_add_f32_e32 v142, v142, v143
	v_mov_b32_e32 v143, v142
	s_nop 1
	v_permlane32_swap_b32_e32 v142, v143
	v_add_f32_e32 v142, v142, v143
	v_fmamk_f32 v142, v142, 0x3a000000, v174
	v_mul_f32_e32 v143, 0x4b800000, v142
	v_cmp_gt_f32_e32 vcc, s9, v142
	s_nop 1
	v_cndmask_b32_e32 v142, v142, v143, vcc
	v_rsq_f32_e32 v142, v142
	s_nop 0
	v_mul_f32_e32 v143, 0x45800000, v142
	v_cndmask_b32_e32 v142, v142, v143, vcc
	v_pk_mul_f32 v[38:39], v[38:39], v[142:143] op_sel_hi:[1,0]
	v_pk_mul_f32 v[36:37], v[36:37], v[142:143] op_sel_hi:[1,0]
	v_pk_mul_f32 v[30:31], v[30:31], v[142:143] op_sel_hi:[1,0]
	v_pk_mul_f32 v[28:29], v[28:29], v[142:143] op_sel_hi:[1,0]
	v_pk_mul_f32 v[22:23], v[22:23], v[142:143] op_sel_hi:[1,0]
	v_pk_mul_f32 v[20:21], v[20:21], v[142:143] op_sel_hi:[1,0]
	v_pk_mul_f32 v[18:19], v[18:19], v[142:143] op_sel_hi:[1,0]
	v_pk_mul_f32 v[16:17], v[16:17], v[142:143] op_sel_hi:[1,0]
	v_pk_mul_f32 v[46:47], v[46:47], v[142:143] op_sel_hi:[1,0]
	v_pk_mul_f32 v[44:45], v[44:45], v[142:143] op_sel_hi:[1,0]
	v_pk_mul_f32 v[42:43], v[42:43], v[142:143] op_sel_hi:[1,0]
	v_pk_mul_f32 v[40:41], v[40:41], v[142:143] op_sel_hi:[1,0]
	v_pk_mul_f32 v[34:35], v[34:35], v[142:143] op_sel_hi:[1,0]
	v_pk_mul_f32 v[32:33], v[32:33], v[142:143] op_sel_hi:[1,0]
	v_pk_mul_f32 v[26:27], v[26:27], v[142:143] op_sel_hi:[1,0]
	v_pk_mul_f32 v[24:25], v[24:25], v[142:143] op_sel_hi:[1,0]
	v_pk_mul_f32 v[36:37], v[48:49], v[36:37]
	v_pk_mul_f32 v[38:39], v[50:51], v[38:39]
	v_pk_mul_f32 v[28:29], v[52:53], v[28:29]
	v_pk_mul_f32 v[30:31], v[54:55], v[30:31]
	v_pk_mul_f32 v[20:21], v[56:57], v[20:21]
	v_pk_mul_f32 v[22:23], v[58:59], v[22:23]
	v_pk_mul_f32 v[16:17], v[60:61], v[16:17]
	v_pk_mul_f32 v[18:19], v[62:63], v[18:19]
	v_pk_mul_f32 v[44:45], v[80:81], v[44:45]
	v_pk_mul_f32 v[46:47], v[82:83], v[46:47]
	v_pk_mul_f32 v[40:41], v[84:85], v[40:41]
	v_pk_mul_f32 v[42:43], v[86:87], v[42:43]
	v_pk_mul_f32 v[32:33], v[88:89], v[32:33]
	v_pk_mul_f32 v[34:35], v[90:91], v[34:35]
	v_pk_mul_f32 v[24:25], v[92:93], v[24:25]
	v_pk_mul_f32 v[26:27], v[94:95], v[26:27]
	v_pk_fma_f32 v[6:7], v[162:163], v[38:39], v[6:7]
	v_pk_fma_f32 v[4:5], v[164:165], v[36:37], v[4:5]
	v_pk_fma_f32 v[2:3], v[122:123], v[30:31], v[2:3]
	v_pk_fma_f32 v[0:1], v[120:121], v[28:29], v[0:1]
	v_pk_fma_f32 v[14:15], v[118:119], v[22:23], v[14:15]
	v_pk_fma_f32 v[12:13], v[116:117], v[20:21], v[12:13]
	v_pk_fma_f32 v[10:11], v[114:115], v[18:19], v[10:11]
	v_pk_fma_f32 v[8:9], v[112:113], v[16:17], v[8:9]
	v_pk_fma_f32 v[16:17], v[110:111], v[46:47], v[70:71]
	v_pk_fma_f32 v[18:19], v[108:109], v[44:45], v[68:69]
	v_pk_fma_f32 v[20:21], v[106:107], v[42:43], v[66:67]
	v_pk_fma_f32 v[22:23], v[104:105], v[40:41], v[64:65]
	s_waitcnt vmcnt(1)
	v_pk_fma_f32 v[28:29], v[102:103], v[34:35], v[78:79]
	v_pk_fma_f32 v[30:31], v[100:101], v[32:33], v[76:77]
	s_waitcnt vmcnt(0)
	v_pk_fma_f32 v[26:27], v[98:99], v[26:27], v[74:75]
	v_pk_fma_f32 v[24:25], v[96:97], v[24:25], v[72:73]
	v_bfe_u32 v32, v4, 16, 1
	v_bfe_u32 v34, v6, 16, 1
	v_bfe_u32 v33, v5, 16, 1
	v_bfe_u32 v35, v7, 16, 1
	v_bfe_u32 v36, v0, 16, 1
	v_bfe_u32 v37, v1, 16, 1
	v_bfe_u32 v38, v2, 16, 1
	v_bfe_u32 v40, v12, 16, 1
	v_bfe_u32 v41, v13, 16, 1
	v_bfe_u32 v42, v14, 16, 1
	v_bfe_u32 v43, v15, 16, 1
	v_bfe_u32 v44, v8, 16, 1
	v_bfe_u32 v46, v10, 16, 1
	v_bfe_u32 v48, v18, 16, 1
	v_bfe_u32 v49, v19, 16, 1
	v_bfe_u32 v50, v16, 16, 1
	v_bfe_u32 v52, v22, 16, 1
	v_bfe_u32 v53, v23, 16, 1
	v_bfe_u32 v54, v20, 16, 1
	v_bfe_u32 v56, v30, 16, 1
	v_bfe_u32 v58, v28, 16, 1
	v_bfe_u32 v60, v24, 16, 1
	v_bfe_u32 v62, v26, 16, 1
	v_add3_u32 v4, v4, v32, s10
	v_add3_u32 v6, v6, v34, s10
	v_bfe_u32 v39, v3, 16, 1
	v_bfe_u32 v45, v9, 16, 1
	v_bfe_u32 v47, v11, 16, 1
	v_bfe_u32 v51, v17, 16, 1
	v_bfe_u32 v55, v21, 16, 1
	v_bfe_u32 v57, v31, 16, 1
	v_bfe_u32 v59, v29, 16, 1
	v_bfe_u32 v61, v25, 16, 1
	v_bfe_u32 v63, v27, 16, 1
	v_add3_u32 v5, v5, v33, s10
	v_add3_u32 v7, v7, v35, s10
	v_add3_u32 v0, v0, v36, s10
	v_add3_u32 v32, v1, v37, s10
	v_add3_u32 v1, v2, v38, s10
	v_add3_u32 v2, v12, v40, s10
	v_add3_u32 v12, v13, v41, s10
	v_add3_u32 v13, v14, v42, s10
	v_add3_u32 v14, v15, v43, s10
	v_add3_u32 v8, v8, v44, s10
	v_add3_u32 v10, v10, v46, s10
	v_add3_u32 v15, v18, v48, s10
	v_add3_u32 v18, v19, v49, s10
	v_add3_u32 v16, v16, v50, s10
	v_add3_u32 v19, v22, v52, s10
	v_add3_u32 v22, v23, v53, s10
	v_add3_u32 v20, v20, v54, s10
	v_add3_u32 v23, v30, v56, s10
	v_add3_u32 v28, v28, v58, s10
	v_add3_u32 v24, v24, v60, s10
	v_add3_u32 v26, v26, v62, s10
	v_lshrrev_b32_e32 v4, 16, v4
	v_lshrrev_b32_e32 v6, 16, v6
	v_add3_u32 v3, v3, v39, s10
	v_add3_u32 v9, v9, v45, s10
	v_add3_u32 v11, v11, v47, s10
	v_add3_u32 v17, v17, v51, s10
	v_add3_u32 v21, v21, v55, s10
	v_add3_u32 v30, v31, v57, s10
	v_add3_u32 v29, v29, v59, s10
	v_add3_u32 v25, v25, v61, s10
	v_add3_u32 v27, v27, v63, s10
	v_lshrrev_b32_e32 v31, 16, v0
	v_lshrrev_b32_e32 v33, 16, v1
	v_lshrrev_b32_e32 v34, 16, v2
	v_lshrrev_b32_e32 v13, 16, v13
	v_lshrrev_b32_e32 v8, 16, v8
	v_lshrrev_b32_e32 v10, 16, v10
	v_lshrrev_b32_e32 v15, 16, v15
	v_lshrrev_b32_e32 v16, 16, v16
	v_lshrrev_b32_e32 v19, 16, v19
	v_lshrrev_b32_e32 v20, 16, v20
	v_lshrrev_b32_e32 v23, 16, v23
	v_lshrrev_b32_e32 v28, 16, v28
	v_lshrrev_b32_e32 v24, 16, v24
	v_lshrrev_b32_e32 v26, 16, v26
	v_and_or_b32 v0, v5, s11, v4
	v_and_or_b32 v1, v7, s11, v6
	v_and_or_b32 v2, v32, s11, v31
	v_and_or_b32 v3, v3, s11, v33
	v_and_or_b32 v4, v12, s11, v34
	v_and_or_b32 v5, v14, s11, v13
	v_and_or_b32 v6, v9, s11, v8
	v_and_or_b32 v7, v11, s11, v10
	v_and_or_b32 v8, v18, s11, v15
	v_and_or_b32 v9, v17, s11, v16
	v_and_or_b32 v10, v22, s11, v19
	v_and_or_b32 v11, v21, s11, v20
	v_and_or_b32 v12, v30, s11, v23
	v_and_or_b32 v13, v29, s11, v28
	v_and_or_b32 v14, v25, s11, v24
	v_and_or_b32 v15, v27, s11, v26
	global_store_dwordx2 v[140:141], v[0:1], off offset:-3584
	global_store_dwordx2 v[140:141], v[2:3], off offset:-3072
	global_store_dwordx2 v[140:141], v[4:5], off offset:-2560
	global_store_dwordx2 v[140:141], v[6:7], off offset:-2048
	global_store_dwordx2 v[140:141], v[8:9], off offset:-1536
	global_store_dwordx2 v[140:141], v[10:11], off offset:-1024
	global_store_dwordx2 v[140:141], v[12:13], off offset:-512
	global_store_dwordx2 v[140:141], v[14:15], off
	v_lshl_add_u64 v[140:141], v[140:141], 0, s[6:7]
	s_cbranch_scc0 .LBB0_119

.LBB0_486:
	s_or_b64 exec, exec, s[0:1]
	v_sub_f32_e32 v37, v37, v38
	v_sub_f32_e32 v36, v36, v38
	v_mul_f32_e32 v37, 0x3fb8aa3b, v37
	v_mul_f32_e32 v36, 0x3fb8aa3b, v36
	v_exp_f32_e32 v37, v37
	v_exp_f32_e32 v36, v36
	v_and_b32_e32 v47, 0xffff0000, v1
	v_and_b32_e32 v46, 0xffff0000, v0
	v_mul_f32_e32 v37, 0x3db504f3, v37
	v_mul_f32_e32 v36, 0x3db504f3, v36
	ds_bpermute_b32 v38, v111, v37
	ds_bpermute_b32 v39, v111, v36
	ds_bpermute_b32 v40, v112, v37
	ds_bpermute_b32 v42, v113, v37
	ds_bpermute_b32 v37, v114, v37
	ds_bpermute_b32 v44, v114, v36
	ds_bpermute_b32 v41, v112, v36
	ds_bpermute_b32 v43, v113, v36
	s_waitcnt lgkmcnt(6)
	v_cndmask_b32_e64 v36, v39, v38, s[20:21]
	v_lshlrev_b32_e32 v39, 16, v1
	v_lshlrev_b32_e32 v38, 16, v0
	v_lshlrev_b32_e32 v49, 16, v3
	v_lshlrev_b32_e32 v48, 16, v2
	v_and_b32_e32 v51, 0xffff0000, v3
	v_and_b32_e32 v50, 0xffff0000, v2
	s_waitcnt lgkmcnt(2)
	v_cndmask_b32_e64 v44, v44, v37, s[20:21]
	v_pk_mul_f32 v[38:39], v[36:37], v[38:39] op_sel_hi:[0,1]
	v_pk_mul_f32 v[46:47], v[36:37], v[46:47] op_sel_hi:[0,1]
	v_pk_mul_f32 v[48:49], v[36:37], v[48:49] op_sel_hi:[0,1]
	v_pk_mul_f32 v[36:37], v[36:37], v[50:51] op_sel_hi:[0,1]
	s_waitcnt lgkmcnt(1)
	v_cndmask_b32_e64 v40, v41, v40, s[20:21]
	s_waitcnt lgkmcnt(0)
	v_cndmask_b32_e64 v42, v43, v42, s[20:21]
	s_nop 0
	s_nop 0
	v_bfe_u32 v45, v47, 16, 1
	v_bfe_u32 v50, v46, 16, 1
	v_add3_u32 v46, v46, v50, s65
	v_add3_u32 v45, v47, v45, s65
	v_bfe_u32 v41, v38, 16, 1
	v_bfe_u32 v43, v39, 16, 1
	v_add3_u32 v39, v39, v43, s65
	v_add3_u32 v38, v38, v41, s65
	v_lshrrev_b32_e32 v41, 16, v38
	v_lshrrev_b32_e32 v43, 16, v39
	v_cvt_pk_bf16_f32 v39, v49, v37
	v_cvt_pk_bf16_f32 v38, v48, v36
	v_and_or_b32 v37, v45, s61, v43
	v_and_or_b32 v36, v46, s61, v41
	s_barrier
	ds_write_b128 v135, v[36:39]
	ds_write_b128 v135, v[4:7] offset:32768
	v_lshlrev_b32_e32 v37, 16, v9
	v_lshlrev_b32_e32 v36, 16, v8
	v_and_b32_e32 v39, 0xffff0000, v9
	v_and_b32_e32 v38, 0xffff0000, v8
	v_lshlrev_b32_e32 v47, 16, v11
	v_lshlrev_b32_e32 v46, 16, v10
	v_and_b32_e32 v49, 0xffff0000, v11
	v_and_b32_e32 v48, 0xffff0000, v10
	v_pk_mul_f32 v[36:37], v[40:41], v[36:37] op_sel_hi:[0,1]
	v_pk_mul_f32 v[38:39], v[40:41], v[38:39] op_sel_hi:[0,1]
	v_pk_mul_f32 v[46:47], v[40:41], v[46:47] op_sel_hi:[0,1]
	v_pk_mul_f32 v[40:41], v[40:41], v[48:49] op_sel_hi:[0,1]
	v_bfe_u32 v43, v41, 16, 1
	v_bfe_u32 v45, v40, 16, 1
	v_bfe_u32 v48, v39, 16, 1
	v_bfe_u32 v49, v38, 16, 1
	v_add3_u32 v49, v38, v49, s65
	v_add3_u32 v48, v39, v48, s65
	v_add3_u32 v38, v40, v45, s65
	v_add3_u32 v39, v41, v43, s65
	v_bfe_u32 v40, v36, 16, 1
	v_bfe_u32 v41, v37, 16, 1
	v_bfe_u32 v43, v46, 16, 1
	v_bfe_u32 v45, v47, 16, 1
	v_add3_u32 v45, v47, v45, s65
	v_add3_u32 v43, v46, v43, s65
	v_add3_u32 v37, v37, v41, s65
	v_add3_u32 v36, v36, v40, s65
	v_lshrrev_b32_e32 v36, 16, v36
	v_lshrrev_b32_e32 v37, 16, v37
	v_lshrrev_b32_e32 v40, 16, v43
	v_lshrrev_b32_e32 v41, 16, v45
	v_and_or_b32 v39, v39, s61, v41
	v_and_or_b32 v38, v38, s61, v40
	v_and_or_b32 v37, v48, s61, v37
	v_and_or_b32 v36, v49, s61, v36
	ds_write_b128 v135, v[36:39] offset:8192
	ds_write_b128 v135, v[12:15] offset:40960
	v_lshlrev_b32_e32 v37, 16, v17
	v_lshlrev_b32_e32 v36, 16, v16
	v_and_b32_e32 v39, 0xffff0000, v17
	v_and_b32_e32 v38, 0xffff0000, v16
	v_lshlrev_b32_e32 v41, 16, v19
	v_lshlrev_b32_e32 v40, 16, v18
	v_and_b32_e32 v47, 0xffff0000, v19
	v_and_b32_e32 v46, 0xffff0000, v18
	v_pk_mul_f32 v[36:37], v[42:43], v[36:37] op_sel_hi:[0,1]
	v_pk_mul_f32 v[38:39], v[42:43], v[38:39] op_sel_hi:[0,1]
	v_pk_mul_f32 v[40:41], v[42:43], v[40:41] op_sel_hi:[0,1]
	v_pk_mul_f32 v[42:43], v[42:43], v[46:47] op_sel_hi:[0,1]
	v_bfe_u32 v45, v43, 16, 1
	v_bfe_u32 v46, v42, 16, 1
	v_bfe_u32 v47, v39, 16, 1
	v_bfe_u32 v48, v38, 16, 1
	v_add3_u32 v48, v38, v48, s65
	v_add3_u32 v47, v39, v47, s65
	v_add3_u32 v38, v42, v46, s65
	v_add3_u32 v39, v43, v45, s65
	v_bfe_u32 v42, v36, 16, 1
	v_bfe_u32 v43, v37, 16, 1
	v_bfe_u32 v45, v40, 16, 1
	v_bfe_u32 v46, v41, 16, 1
	v_add3_u32 v41, v41, v46, s65
	v_add3_u32 v40, v40, v45, s65
	v_add3_u32 v37, v37, v43, s65
	v_add3_u32 v36, v36, v42, s65
	v_lshrrev_b32_e32 v36, 16, v36
	v_lshrrev_b32_e32 v37, 16, v37
	v_lshrrev_b32_e32 v40, 16, v40
	v_lshrrev_b32_e32 v41, 16, v41
	v_and_or_b32 v39, v39, s61, v41
	v_and_or_b32 v38, v38, s61, v40
	v_and_or_b32 v37, v47, s61, v37
	v_and_or_b32 v36, v48, s61, v36
	ds_write_b128 v135, v[36:39] offset:16384
	ds_write_b128 v135, v[20:23] offset:49152
	v_and_b32_e32 v39, 0xffff0000, v25
	v_and_b32_e32 v38, 0xffff0000, v24
	v_and_b32_e32 v43, 0xffff0000, v27
	v_and_b32_e32 v42, 0xffff0000, v26
	v_lshlrev_b32_e32 v37, 16, v25
	v_lshlrev_b32_e32 v36, 16, v24
	v_pk_mul_f32 v[38:39], v[44:45], v[38:39] op_sel_hi:[0,1]
	v_lshlrev_b32_e32 v41, 16, v27
	v_lshlrev_b32_e32 v40, 16, v26
	v_pk_mul_f32 v[42:43], v[44:45], v[42:43] op_sel_hi:[0,1]
	v_pk_mul_f32 v[36:37], v[44:45], v[36:37] op_sel_hi:[0,1]
	v_pk_mul_f32 v[40:41], v[44:45], v[40:41] op_sel_hi:[0,1]
	v_bfe_u32 v44, v43, 16, 1
	v_bfe_u32 v45, v42, 16, 1
	v_bfe_u32 v46, v39, 16, 1
	v_bfe_u32 v47, v38, 16, 1
	v_add3_u32 v47, v38, v47, s65
	v_add3_u32 v46, v39, v46, s65
	v_add3_u32 v38, v42, v45, s65
	v_add3_u32 v39, v43, v44, s65
	v_bfe_u32 v42, v36, 16, 1
	v_bfe_u32 v43, v37, 16, 1
	v_bfe_u32 v44, v40, 16, 1
	v_bfe_u32 v45, v41, 16, 1
	s_add_i32 s24, s24, s96
	v_add3_u32 v41, v41, v45, s65
	v_add3_u32 v40, v40, v44, s65
	v_add3_u32 v37, v37, v43, s65
	v_add3_u32 v36, v36, v42, s65
	s_cmpk_gt_i32 s24, 0x3ff
	v_lshrrev_b32_e32 v36, 16, v36
	v_lshrrev_b32_e32 v37, 16, v37
	v_lshrrev_b32_e32 v40, 16, v40
	v_lshrrev_b32_e32 v41, 16, v41
	s_cselect_b64 s[0:1], -1, 0
	v_and_or_b32 v39, v39, s61, v41
	v_and_or_b32 v38, v38, s61, v40
	v_and_or_b32 v37, v46, s61, v37
	v_and_or_b32 v36, v47, s61, v36
	s_and_b64 vcc, exec, s[0:1]
	ds_write_b128 v135, v[36:39] offset:24576
	ds_write_b128 v135, v[28:31] offset:57344
	s_waitcnt lgkmcnt(0)
	s_barrier
	s_cbranch_vccnz .LBB0_488
	s_ashr_i32 s3, s24, 31
	s_lshr_b32 s3, s3, 22
	s_add_i32 s3, s24, s3
	s_and_b32 s3, s3, 0xfffffc00
	s_sub_i32 s3, s24, s3
	s_lshl_b32 s4, s3, 4
	s_and_b32 s41, s4, 0xffffff80
	v_add_u32_e32 v26, s41, v92
	v_mov_b64_e32 v[24:25], s[28:29]
	s_bfe_u32 s25, s3, 0x20001
	v_mad_i64_i32 v[0:1], s[4:5], v26, s91, v[24:25]
	s_lshl_b32 s4, s25, 8
	s_mov_b32 s5, s48
	v_lshl_add_u64 v[0:1], v[0:1], 0, s[4:5]
	v_add_u32_e32 v8, 32, v26
	v_lshl_add_u64 v[0:1], v[0:1], 0, v[178:179]
	s_mov_b32 s42, 0x1b801000
	v_mad_i64_i32 v[8:9], s[26:27], v8, s91, v[24:25]
	v_add_co_u32_e32 v4, vcc, s42, v0
	v_lshl_add_u64 v[8:9], v[8:9], 0, s[4:5]
	v_add_u32_e32 v16, 64, v26
	v_addc_co_u32_e32 v5, vcc, 0, v1, vcc
	v_lshl_add_u64 v[8:9], v[8:9], 0, v[178:179]
	v_mad_i64_i32 v[16:17], s[26:27], v16, s91, v[24:25]
	v_add_co_u32_e32 v12, vcc, s42, v8
	v_lshl_add_u64 v[16:17], v[16:17], 0, s[4:5]
	v_add_u32_e32 v26, 0x60, v26
	v_or_b32_e32 v36, s41, v93
	v_addc_co_u32_e32 v13, vcc, 0, v9, vcc
	v_lshl_add_u64 v[16:17], v[16:17], 0, v[178:179]
	v_mad_i64_i32 v[24:25], s[26:27], v26, s91, v[24:25]
	v_ashrrev_i32_e32 v37, 31, v36
	v_add_co_u32_e32 v20, vcc, s42, v16
	v_lshl_add_u64 v[24:25], v[24:25], 0, s[4:5]
	v_lshlrev_b64 v[36:37], 6, v[36:37]
	s_lshl_b32 s3, s3, 5
	v_addc_co_u32_e32 v21, vcc, 0, v17, vcc
	v_lshl_add_u64 v[24:25], v[24:25], 0, v[178:179]
	v_lshl_add_u64 v[36:37], s[34:35], 0, v[36:37]
	s_and_b32 s4, s3, 32
	v_add_co_u32_e32 v28, vcc, s42, v24
	v_lshl_add_u64 v[36:37], v[36:37], 0, s[4:5]
	s_lshl_b32 s4, s25, 2
	v_addc_co_u32_e32 v29, vcc, 0, v25, vcc
	v_lshl_add_u64 v[36:37], v[36:37], 0, s[4:5]
	global_load_dwordx4 v[0:3], v[4:5], off
	s_nop 0
	global_load_dwordx4 v[4:7], v[4:5], off offset:1024
	s_nop 0
	global_load_dwordx4 v[8:11], v[12:13], off
	s_nop 0
	global_load_dwordx4 v[12:15], v[12:13], off offset:1024
	s_nop 0
	global_load_dwordx4 v[16:19], v[20:21], off
	s_nop 0
	global_load_dwordx4 v[20:23], v[20:21], off offset:1024
	s_nop 0
	global_load_dwordx4 v[24:27], v[28:29], off
	s_nop 0
	global_load_dwordx4 v[28:31], v[28:29], off offset:1024
	s_nop 0
	global_load_dword v107, v[36:37], off
	global_load_dword v108, v[36:37], off offset:16
	global_load_dword v109, v[36:37], off offset:64
	global_load_dword v110, v[36:37], off offset:80

.LBB0_921:
	s_waitcnt vmcnt(7)
	v_and_b32_e32 v181, 0xffff0000, v208
	v_and_b32_e32 v183, 0xffff0000, v209
	v_lshlrev_b32_e32 v180, 16, v208
	v_lshlrev_b32_e32 v182, 16, v209
	v_mul_f32_e32 v208, v183, v183
	s_waitcnt vmcnt(6)
	v_lshlrev_b32_e32 v211, 16, v207
	v_lshlrev_b32_e32 v210, 16, v206
	v_and_b32_e32 v207, 0xffff0000, v207
	v_and_b32_e32 v206, 0xffff0000, v206
	s_waitcnt vmcnt(4)
	v_lshlrev_b32_e32 v233, 16, v202
	v_mul_f32_e32 v232, v181, v181
	v_pk_fma_f32 v[208:209], v[182:183], v[182:183], v[208:209] op_sel_hi:[1,1,0]
	v_pk_mul_f32 v[212:213], v[206:207], v[206:207]
	v_pk_fma_f32 v[236:237], v[180:181], v[180:181], v[232:233] op_sel_hi:[1,1,0]
	v_pk_fma_f32 v[212:213], v[210:211], v[210:211], v[212:213]
	v_and_b32_e32 v235, 0xffff0000, v202
	v_mov_b32_e32 v232, v236
	v_mov_b32_e32 v238, v208
	v_mov_b32_e32 v239, v233
	v_mul_f32_e32 v234, v235, v235
	v_pk_add_f32 v[208:209], v[236:237], v[208:209]
	v_pk_mul_f32 v[236:237], v[232:233], v[238:239]
	v_pk_add_f32 v[212:213], v[212:213], v[212:213] op_sel:[0,1] op_sel_hi:[1,0]
	v_lshlrev_b32_e32 v230, 16, v204
	v_and_b32_e32 v231, 0xffff0000, v204
	v_lshlrev_b32_e32 v204, 16, v205
	v_and_b32_e32 v205, 0xffff0000, v205
	v_mov_b32_e32 v209, v237
	v_mov_b32_e32 v213, v234
	v_lshlrev_b32_e32 v202, 16, v203
	v_and_b32_e32 v203, 0xffff0000, v203
	v_pk_add_f32 v[208:209], v[208:209], v[212:213]
	v_mul_f32_e32 v212, v231, v231
	v_mul_f32_e32 v232, v205, v205
	v_mul_f32_e32 v240, v202, v202
	v_mul_f32_e32 v241, v203, v203
	v_pk_fma_f32 v[212:213], v[230:231], v[230:231], v[212:213] op_sel_hi:[1,1,0]
	v_pk_fma_f32 v[236:237], v[204:205], v[204:205], v[232:233] op_sel_hi:[1,1,0]
	v_mov_b32_e32 v213, v240
	v_mov_b32_e32 v237, v241
	v_pk_add_f32 v[212:213], v[212:213], v[236:237]
	s_waitcnt vmcnt(2)
	v_lshlrev_b32_e32 v239, 16, v199
	v_pk_add_f32 v[208:209], v[208:209], v[212:213]
	v_lshlrev_b32_e32 v213, 16, v201
	v_lshlrev_b32_e32 v212, 16, v200
	v_and_b32_e32 v201, 0xffff0000, v201
	v_and_b32_e32 v200, 0xffff0000, v200
	v_pk_mul_f32 v[236:237], v[200:201], v[200:201]
	v_lshlrev_b32_e32 v238, 16, v198
	v_pk_fma_f32 v[236:237], v[212:213], v[212:213], v[236:237]
	v_and_b32_e32 v199, 0xffff0000, v199
	v_pk_add_f32 v[236:237], v[236:237], v[236:237] op_sel:[0,1] op_sel_hi:[1,0]
	v_and_b32_e32 v198, 0xffff0000, v198
	s_waitcnt vmcnt(0)
	v_lshlrev_b32_e32 v245, 16, v194
	v_pk_add_f32 v[208:209], v[208:209], v[208:209] op_sel:[0,1] op_sel_hi:[1,0]
	v_pk_mul_f32 v[240:241], v[198:199], v[198:199]
	v_mov_b32_e32 v244, v208
	v_mov_b32_e32 v248, v236
	v_mov_b32_e32 v249, v245
	v_pk_fma_f32 v[240:241], v[238:239], v[238:239], v[240:241]
	v_and_b32_e32 v247, 0xffff0000, v194
	v_pk_add_f32 v[208:209], v[208:209], v[236:237]
	v_pk_mul_f32 v[236:237], v[244:245], v[248:249]
	v_and_b32_e32 v243, 0xffff0000, v196
	v_mul_f32_e32 v232, v247, v247
	v_mov_b32_e32 v209, v237
	v_pk_add_f32 v[236:237], v[240:241], v[240:241] op_sel:[0,1] op_sel_hi:[1,0]
	v_lshlrev_b32_e32 v242, 16, v196
	v_lshlrev_b32_e32 v196, 16, v197
	v_and_b32_e32 v197, 0xffff0000, v197
	v_mov_b32_e32 v237, v232
	v_mul_f32_e32 v232, v243, v243
	v_lshlrev_b32_e32 v194, 16, v195
	v_and_b32_e32 v195, 0xffff0000, v195
	v_pk_add_f32 v[208:209], v[208:209], v[236:237]
	v_pk_fma_f32 v[236:237], v[242:243], v[242:243], v[232:233] op_sel_hi:[1,1,0]
	v_mul_f32_e32 v232, v197, v197
	v_mul_f32_e32 v234, v194, v194
	v_mul_f32_e32 v246, v195, v195
	v_pk_fma_f32 v[240:241], v[196:197], v[196:197], v[232:233] op_sel_hi:[1,1,0]
	v_mov_b32_e32 v237, v234
	v_mov_b32_e32 v241, v246
	v_pk_add_f32 v[236:237], v[236:237], v[240:241]
	v_mov_b32_e32 v234, v233
	v_pk_add_f32 v[208:209], v[208:209], v[236:237]
	v_mov_b32_e32 v246, v245
	v_add_f32_e32 v208, v208, v209
	s_add_u32 s24, s24, 1
	s_addc_u32 s25, s25, 0
	s_add_u32 s26, s26, 0x1000
	s_addc_u32 s27, s27, 0
	s_waitcnt lgkmcnt(0)
	s_add_i32 s35, s35, 1
	s_cmp_ge_i32 s35, s34
	s_nop 1
	v_add_f32_dpp v208, v208, v208 quad_perm:[1,0,3,2] row_mask:0xf bank_mask:0xf
	s_nop 1
	v_add_f32_dpp v208, v208, v208 quad_perm:[2,3,0,1] row_mask:0xf bank_mask:0xf
	s_nop 1
	v_add_f32_dpp v208, v208, v208 row_half_mirror row_mask:0xf bank_mask:0xf
	s_nop 1
	v_add_f32_dpp v208, v208, v208 row_mirror row_mask:0xf bank_mask:0xf
	v_mov_b32_e32 v209, v208
	s_nop 1
	v_permlane16_swap_b32_e32 v208, v209
	v_add_f32_e32 v208, v208, v209
	v_mov_b32_e32 v209, v208
	s_nop 1
	v_permlane32_swap_b32_e32 v208, v209
	v_add_f32_e32 v208, v208, v209
	v_fmamk_f32 v208, v208, 0x3a000000, v252
	v_mul_f32_e32 v209, 0x4b800000, v208
	v_cmp_gt_f32_e32 vcc, s88, v208
	s_nop 1
	v_cndmask_b32_e32 v208, v208, v209, vcc
	v_rsq_f32_e32 v208, v208
	s_nop 0
	v_mul_f32_e32 v209, 0x45800000, v208
	v_cndmask_b32_e32 v208, v208, v209, vcc
	v_pk_mul_f32 v[180:181], v[208:209], v[180:181] op_sel_hi:[0,1]
	v_pk_mul_f32 v[180:181], v[32:33], v[180:181]
	v_pk_mul_f32 v[182:183], v[208:209], v[182:183] op_sel_hi:[0,1]
	v_pk_fma_f32 v[0:1], v[64:65], v[180:181], v[0:1]
	v_mov_b32_e32 v180, v211
	v_mov_b32_e32 v181, v207
	v_pk_mul_f32 v[180:181], v[208:209], v[180:181] op_sel_hi:[0,1]
	v_pk_mul_f32 v[180:181], v[38:39], v[180:181]
	v_pk_mul_f32 v[182:183], v[34:35], v[182:183]
	v_pk_fma_f32 v[6:7], v[70:71], v[180:181], v[6:7]
	v_pk_mul_f32 v[180:181], v[208:209], v[204:205] op_sel_hi:[0,1]
	v_pk_mul_f32 v[180:181], v[42:43], v[180:181]
	v_mov_b32_e32 v211, v206
	v_pk_fma_f32 v[10:11], v[74:75], v[180:181], v[10:11]
	v_pk_mul_f32 v[180:181], v[202:203], v[208:209] op_sel_hi:[1,0]
	v_pk_fma_f32 v[2:3], v[66:67], v[182:183], v[2:3]
	v_pk_mul_f32 v[180:181], v[46:47], v[180:181]
	v_pk_mul_f32 v[182:183], v[208:209], v[210:211] op_sel_hi:[0,1]
	v_pk_fma_f32 v[14:15], v[78:79], v[180:181], v[14:15]
	v_mov_b32_e32 v180, v213
	v_mov_b32_e32 v181, v201
	v_pk_mul_f32 v[182:183], v[36:37], v[182:183]
	v_pk_mul_f32 v[180:181], v[208:209], v[180:181] op_sel_hi:[0,1]
	v_pk_fma_f32 v[4:5], v[68:69], v[182:183], v[4:5]
	v_pk_mul_f32 v[182:183], v[208:209], v[230:231] op_sel_hi:[0,1]
	v_pk_mul_f32 v[180:181], v[50:51], v[180:181]
	v_pk_mul_f32 v[182:183], v[40:41], v[182:183]
	v_pk_fma_f32 v[18:19], v[82:83], v[180:181], v[18:19]
	v_mov_b32_e32 v180, v239
	v_mov_b32_e32 v181, v199
	v_pk_fma_f32 v[8:9], v[72:73], v[182:183], v[8:9]
	v_pk_mul_f32 v[182:183], v[234:235], v[208:209] op_sel_hi:[1,0]
	v_pk_mul_f32 v[180:181], v[208:209], v[180:181] op_sel_hi:[0,1]
	v_pk_mul_f32 v[182:183], v[44:45], v[182:183]
	v_mov_b32_e32 v213, v200
	v_pk_mul_f32 v[180:181], v[54:55], v[180:181]
	v_pk_fma_f32 v[12:13], v[76:77], v[182:183], v[12:13]
	v_pk_mul_f32 v[182:183], v[208:209], v[212:213] op_sel_hi:[0,1]
	v_pk_fma_f32 v[22:23], v[86:87], v[180:181], v[22:23]
	v_pk_mul_f32 v[180:181], v[208:209], v[196:197] op_sel_hi:[0,1]
	v_pk_mul_f32 v[182:183], v[48:49], v[182:183]
	v_mov_b32_e32 v239, v198
	v_pk_mul_f32 v[180:181], v[58:59], v[180:181]
	v_pk_fma_f32 v[16:17], v[80:81], v[182:183], v[16:17]
	v_pk_mul_f32 v[182:183], v[208:209], v[238:239] op_sel_hi:[0,1]
	v_pk_fma_f32 v[26:27], v[90:91], v[180:181], v[26:27]
	v_pk_mul_f32 v[180:181], v[194:195], v[208:209] op_sel_hi:[1,0]
	v_pk_mul_f32 v[182:183], v[52:53], v[182:183]
	v_pk_mul_f32 v[180:181], v[62:63], v[180:181]
	v_pk_fma_f32 v[20:21], v[84:85], v[182:183], v[20:21]
	v_pk_mul_f32 v[182:183], v[208:209], v[242:243] op_sel_hi:[0,1]
	v_pk_fma_f32 v[30:31], v[94:95], v[180:181], v[30:31]
	v_pk_mul_f32 v[182:183], v[56:57], v[182:183]
	v_pk_fma_f32 v[24:25], v[88:89], v[182:183], v[24:25]
	v_pk_mul_f32 v[182:183], v[246:247], v[208:209] op_sel_hi:[1,0]
	v_pk_mul_f32 v[182:183], v[60:61], v[182:183]
	v_cvt_pk_bf16_f32 v180, v0, v1
	v_pk_fma_f32 v[28:29], v[92:93], v[182:183], v[28:29]
	v_lshl_add_u64 v[194:195], v[164:165], 0, s[28:29]
	v_cvt_pk_bf16_f32 v181, v2, v3
	global_store_dwordx2 v[194:195], v[180:181], off
	v_cvt_pk_bf16_f32 v180, v4, v5
	v_cvt_pk_bf16_f32 v181, v6, v7
	global_store_dwordx2 v[194:195], v[180:181], off offset:512
	v_cvt_pk_bf16_f32 v180, v8, v9
	v_cvt_pk_bf16_f32 v181, v10, v11
	global_store_dwordx2 v[194:195], v[180:181], off offset:1024
	v_cvt_pk_bf16_f32 v180, v12, v13
	v_cvt_pk_bf16_f32 v181, v14, v15
	global_store_dwordx2 v[194:195], v[180:181], off offset:1536
	v_cvt_pk_bf16_f32 v180, v16, v17
	v_cvt_pk_bf16_f32 v181, v18, v19
	global_store_dwordx2 v[194:195], v[180:181], off offset:2048
	v_cvt_pk_bf16_f32 v180, v20, v21
	v_mov_b32_e32 v196, v1
	v_mov_b32_e32 v197, v5
	v_cvt_pk_bf16_f32 v181, v22, v23
	v_mov_b32_e32 v182, v0
	v_mov_b32_e32 v183, v4
	v_pk_mul_f32 v[196:197], v[196:197], v[196:197]
	v_mov_b32_e32 v198, v3
	v_mov_b32_e32 v199, v7
	v_pk_fma_f32 v[182:183], v[182:183], v[182:183], v[196:197]
	v_mov_b32_e32 v196, v2
	v_mov_b32_e32 v197, v6
	v_pk_mul_f32 v[198:199], v[198:199], v[198:199]
	global_store_dwordx2 v[194:195], v[180:181], off offset:2560
	v_pk_fma_f32 v[196:197], v[196:197], v[196:197], v[198:199]
	v_pk_mul_f32 v[198:199], v[8:9], v[8:9]
	v_pk_add_f32 v[182:183], v[182:183], v[196:197]
	v_pk_mul_f32 v[196:197], v[10:11], v[10:11]
	v_pk_add_f32 v[182:183], v[182:183], v[182:183] op_sel_hi:[0,1]
	v_pk_mov_b32 v[200:201], v[198:199], v[196:197] op_sel:[1,0]
	v_mov_b32_e32 v199, v197
	v_mul_f32_e32 v182, v12, v12
	v_pk_add_f32 v[196:197], v[200:201], v[198:199]
	v_pk_fma_f32 v[198:199], v[12:13], v[12:13], v[182:183] op_sel_hi:[1,1,0]
	v_mul_f32_e32 v182, v14, v14
	v_pk_add_f32 v[196:197], v[196:197], v[196:197] op_sel_hi:[0,1]
	v_pk_fma_f32 v[200:201], v[14:15], v[14:15], v[182:183] op_sel_hi:[1,1,0]
	v_mul_f32_e32 v198, v16, v16
	v_mul_f32_e32 v200, v17, v17
	v_mul_f32_e32 v196, v18, v18
	v_mul_f32_e32 v182, v19, v19
	v_pk_add_f32 v[198:199], v[198:199], v[200:201]
	v_pk_add_f32 v[182:183], v[196:197], v[182:183]
	v_pk_mul_f32 v[196:197], v[22:23], v[22:23]
	v_pk_add_f32 v[182:183], v[198:199], v[182:183]
	v_pk_mul_f32 v[198:199], v[20:21], v[20:21]
	v_pk_add_f32 v[182:183], v[182:183], v[182:183] op_sel_hi:[0,1]
	v_pk_mov_b32 v[200:201], v[198:199], v[196:197] op_sel:[1,0]
	v_mov_b32_e32 v199, v197
	v_mul_f32_e32 v182, v24, v24
	v_pk_add_f32 v[196:197], v[200:201], v[198:199]
	v_pk_fma_f32 v[198:199], v[24:25], v[24:25], v[182:183] op_sel_hi:[1,1,0]
	v_mul_f32_e32 v182, v26, v26
	v_pk_add_f32 v[196:197], v[196:197], v[196:197] op_sel_hi:[0,1]
	v_pk_fma_f32 v[200:201], v[26:27], v[26:27], v[182:183] op_sel_hi:[1,1,0]
	v_mul_f32_e32 v198, v28, v28
	v_mul_f32_e32 v200, v29, v29
	v_mul_f32_e32 v196, v30, v30
	v_mul_f32_e32 v182, v31, v31
	v_pk_add_f32 v[198:199], v[198:199], v[200:201]
	v_pk_add_f32 v[182:183], v[196:197], v[182:183]
	v_pk_add_f32 v[182:183], v[198:199], v[182:183]
	v_add_f32_e32 v182, v182, v183
	v_mov_b64_e32 v[198:199], v[174:175]
	s_waitcnt lgkmcnt(0)
	v_cvt_pk_bf16_f32 v180, v24, v25
	v_mov_b64_e32 v[200:201], v[184:185]
	v_mov_b64_e32 v[202:203], v[186:187]
	v_cvt_pk_bf16_f32 v181, v26, v27
	global_store_dwordx2 v[194:195], v[180:181], off offset:3072
	v_cvt_pk_bf16_f32 v180, v28, v29
	s_nop 0
	s_nop 0
	s_nop 1
	v_add_f32_dpp v181, v182, v182 quad_perm:[1,0,3,2] row_mask:0xf bank_mask:0xf
	s_nop 1
	v_add_f32_dpp v181, v181, v181 quad_perm:[2,3,0,1] row_mask:0xf bank_mask:0xf
	s_nop 1
	v_add_f32_dpp v181, v181, v181 row_half_mirror row_mask:0xf bank_mask:0xf
	s_nop 1
	v_add_f32_dpp v181, v181, v181 row_mirror row_mask:0xf bank_mask:0xf
	v_mov_b32_e32 v182, v181
	s_nop 1
	v_permlane16_swap_b32_e32 v181, v182
	v_add_f32_e32 v181, v181, v182
	v_mov_b32_e32 v182, v181
	s_nop 1
	v_permlane32_swap_b32_e32 v181, v182
	v_add_f32_e32 v181, v181, v182
	v_fmamk_f32 v181, v181, 0x3a000000, v252
	v_mul_f32_e32 v182, 0x4b800000, v181
	v_cmp_gt_f32_e32 vcc, s88, v181
	v_mov_b64_e32 v[204:205], v[188:189]
	v_mov_b64_e32 v[206:207], v[190:191]
	v_cndmask_b32_e32 v181, v181, v182, vcc
	v_rsq_f32_e32 v182, v181
	s_nop 0
	v_cvt_pk_bf16_f32 v181, v30, v31
	global_store_dwordx2 v[194:195], v[180:181], off offset:3584
	v_mul_f32_e32 v180, 0x45800000, v182
	v_cndmask_b32_e32 v180, v182, v180, vcc
	v_pk_mul_f32 v[194:195], v[0:1], v[180:181] op_sel_hi:[1,0]
	v_pk_mul_f32 v[196:197], v[2:3], v[180:181] op_sel_hi:[1,0]
	v_pk_fma_f32 v[194:195], v[132:133], v[194:195], v[96:97]
	v_pk_fma_f32 v[196:197], v[130:131], v[196:197], v[98:99]
	s_nop 0
	s_nop 0
	v_cvt_pk_bf16_f32 v194, v194, v195
	v_lshl_add_u64 v[182:183], v[166:167], 0, s[28:29]
	v_cvt_pk_bf16_f32 v195, v196, v197
	global_store_dwordx2 v[182:183], v[194:195], off
	v_pk_mul_f32 v[194:195], v[4:5], v[180:181] op_sel_hi:[1,0]
	v_pk_mul_f32 v[196:197], v[6:7], v[180:181] op_sel_hi:[1,0]
	v_pk_fma_f32 v[194:195], v[136:137], v[194:195], v[100:101]
	v_pk_fma_f32 v[196:197], v[134:135], v[196:197], v[102:103]
	v_cvt_pk_bf16_f32 v194, v194, v195
	v_cvt_pk_bf16_f32 v195, v196, v197
	global_store_dwordx2 v[182:183], v[194:195], off offset:512
	v_pk_mul_f32 v[194:195], v[8:9], v[180:181] op_sel_hi:[1,0]
	v_pk_mul_f32 v[196:197], v[10:11], v[180:181] op_sel_hi:[1,0]
	v_pk_fma_f32 v[194:195], v[140:141], v[194:195], v[104:105]
	v_pk_fma_f32 v[196:197], v[138:139], v[196:197], v[106:107]
	v_cvt_pk_bf16_f32 v194, v194, v195
	v_cvt_pk_bf16_f32 v195, v196, v197
	global_store_dwordx2 v[182:183], v[194:195], off offset:1024
	v_pk_mul_f32 v[194:195], v[12:13], v[180:181] op_sel_hi:[1,0]
	v_pk_mul_f32 v[196:197], v[14:15], v[180:181] op_sel_hi:[1,0]
	v_pk_fma_f32 v[194:195], v[144:145], v[194:195], v[108:109]
	v_pk_fma_f32 v[196:197], v[142:143], v[196:197], v[110:111]
	v_cvt_pk_bf16_f32 v194, v194, v195
	v_cvt_pk_bf16_f32 v195, v196, v197
	global_store_dwordx2 v[182:183], v[194:195], off offset:1536
	v_pk_mul_f32 v[194:195], v[16:17], v[180:181] op_sel_hi:[1,0]
	v_pk_mul_f32 v[196:197], v[18:19], v[180:181] op_sel_hi:[1,0]
	v_pk_fma_f32 v[194:195], v[148:149], v[194:195], v[112:113]
	v_pk_fma_f32 v[196:197], v[146:147], v[196:197], v[114:115]
	v_cvt_pk_bf16_f32 v194, v194, v195
	v_cvt_pk_bf16_f32 v195, v196, v197
	global_store_dwordx2 v[182:183], v[194:195], off offset:2048
	v_pk_mul_f32 v[194:195], v[20:21], v[180:181] op_sel_hi:[1,0]
	v_pk_mul_f32 v[196:197], v[22:23], v[180:181] op_sel_hi:[1,0]
	v_pk_fma_f32 v[194:195], v[152:153], v[194:195], v[116:117]
	v_pk_fma_f32 v[196:197], v[150:151], v[196:197], v[118:119]
	v_cvt_pk_bf16_f32 v194, v194, v195
	v_cvt_pk_bf16_f32 v195, v196, v197
	global_store_dwordx2 v[182:183], v[194:195], off offset:2560
	v_pk_mul_f32 v[194:195], v[24:25], v[180:181] op_sel_hi:[1,0]
	v_pk_mul_f32 v[196:197], v[26:27], v[180:181] op_sel_hi:[1,0]
	v_pk_fma_f32 v[194:195], v[156:157], v[194:195], v[120:121]
	v_pk_fma_f32 v[196:197], v[154:155], v[196:197], v[122:123]
	v_cvt_pk_bf16_f32 v194, v194, v195
	v_cvt_pk_bf16_f32 v195, v196, v197
	global_store_dwordx2 v[182:183], v[194:195], off offset:3072
	v_pk_mul_f32 v[194:195], v[28:29], v[180:181] op_sel_hi:[1,0]
	v_pk_mul_f32 v[180:181], v[30:31], v[180:181] op_sel_hi:[1,0]
	v_pk_fma_f32 v[194:195], v[160:161], v[194:195], v[124:125]
	v_pk_fma_f32 v[180:181], v[158:159], v[180:181], v[126:127]
	v_cvt_pk_bf16_f32 v194, v194, v195
	v_bfe_u32 v195, v180, 16, 1
	v_add3_u32 v180, v180, v195, s65
	v_bfe_u32 v195, v181, 16, 1
	v_lshrrev_b32_e32 v180, 16, v180
	v_add3_u32 v181, v181, v195, s65
	v_and_or_b32 v195, v181, s61, v180
	global_store_dwordx2 v[182:183], v[194:195], off offset:3584
	v_mov_b64_e32 v[194:195], v[170:171]
	v_mov_b64_e32 v[196:197], v[172:173]
	v_mov_b64_e32 v[208:209], v[192:193]
	s_cbranch_scc1 .LBB0_928

.LBB0_932:
	s_waitcnt vmcnt(23)
	v_lshlrev_b32_e32 v170, 16, v162
	v_and_b32_e32 v171, 0xffff0000, v162
	v_lshlrev_b32_e32 v162, 16, v163
	v_and_b32_e32 v163, 0xffff0000, v163
	v_mul_f32_e32 v172, v163, v163
	s_waitcnt vmcnt(22)
	v_lshlrev_b32_e32 v175, 16, v161
	v_lshlrev_b32_e32 v174, 16, v160
	v_and_b32_e32 v161, 0xffff0000, v161
	v_and_b32_e32 v160, 0xffff0000, v160
	s_waitcnt vmcnt(20)
	v_lshlrev_b32_e32 v185, 16, v156
	v_mul_f32_e32 v184, v171, v171
	v_pk_fma_f32 v[172:173], v[162:163], v[162:163], v[172:173] op_sel_hi:[1,1,0]
	v_pk_mul_f32 v[180:181], v[160:161], v[160:161]
	v_pk_fma_f32 v[188:189], v[170:171], v[170:171], v[184:185] op_sel_hi:[1,1,0]
	v_pk_fma_f32 v[180:181], v[174:175], v[174:175], v[180:181]
	v_and_b32_e32 v187, 0xffff0000, v156
	v_mov_b32_e32 v184, v188
	v_mov_b32_e32 v190, v172
	v_mov_b32_e32 v191, v185
	v_mul_f32_e32 v169, v187, v187
	v_pk_add_f32 v[172:173], v[188:189], v[172:173]
	v_pk_mul_f32 v[188:189], v[184:185], v[190:191]
	v_pk_add_f32 v[180:181], v[180:181], v[180:181] op_sel:[0,1] op_sel_hi:[1,0]
	v_lshlrev_b32_e32 v182, 16, v158
	v_and_b32_e32 v183, 0xffff0000, v158
	v_lshlrev_b32_e32 v158, 16, v159
	v_and_b32_e32 v159, 0xffff0000, v159
	v_mov_b32_e32 v173, v189
	v_mov_b32_e32 v181, v169
	v_lshlrev_b32_e32 v156, 16, v157
	v_and_b32_e32 v157, 0xffff0000, v157
	v_pk_add_f32 v[172:173], v[172:173], v[180:181]
	v_mul_f32_e32 v180, v183, v183
	v_mul_f32_e32 v184, v159, v159
	v_mul_f32_e32 v186, v156, v156
	v_mul_f32_e32 v192, v157, v157
	v_pk_fma_f32 v[180:181], v[182:183], v[182:183], v[180:181] op_sel_hi:[1,1,0]
	v_pk_fma_f32 v[188:189], v[158:159], v[158:159], v[184:185] op_sel_hi:[1,1,0]
	v_mov_b32_e32 v181, v186
	v_mov_b32_e32 v189, v192
	v_pk_add_f32 v[180:181], v[180:181], v[188:189]
	s_waitcnt vmcnt(18)
	v_lshlrev_b32_e32 v191, 16, v153
	v_pk_add_f32 v[172:173], v[172:173], v[180:181]
	v_lshlrev_b32_e32 v181, 16, v155
	v_lshlrev_b32_e32 v180, 16, v154
	v_and_b32_e32 v155, 0xffff0000, v155
	v_and_b32_e32 v154, 0xffff0000, v154
	v_pk_mul_f32 v[188:189], v[154:155], v[154:155]
	v_lshlrev_b32_e32 v190, 16, v152
	v_pk_fma_f32 v[188:189], v[180:181], v[180:181], v[188:189]
	v_and_b32_e32 v153, 0xffff0000, v153
	v_pk_add_f32 v[188:189], v[188:189], v[188:189] op_sel:[0,1] op_sel_hi:[1,0]
	v_and_b32_e32 v152, 0xffff0000, v152
	s_waitcnt vmcnt(16)
	v_lshlrev_b32_e32 v197, 16, v148
	v_pk_add_f32 v[172:173], v[172:173], v[172:173] op_sel:[0,1] op_sel_hi:[1,0]
	v_pk_mul_f32 v[192:193], v[152:153], v[152:153]
	v_mov_b32_e32 v196, v172
	v_mov_b32_e32 v200, v188
	v_mov_b32_e32 v201, v197
	v_pk_fma_f32 v[192:193], v[190:191], v[190:191], v[192:193]
	v_and_b32_e32 v199, 0xffff0000, v148
	v_pk_add_f32 v[172:173], v[172:173], v[188:189]
	v_pk_mul_f32 v[188:189], v[196:197], v[200:201]
	v_and_b32_e32 v195, 0xffff0000, v150
	v_mul_f32_e32 v169, v199, v199
	v_mov_b32_e32 v173, v189
	v_pk_add_f32 v[188:189], v[192:193], v[192:193] op_sel:[0,1] op_sel_hi:[1,0]
	v_lshlrev_b32_e32 v194, 16, v150
	v_lshlrev_b32_e32 v150, 16, v151
	v_and_b32_e32 v151, 0xffff0000, v151
	v_mov_b32_e32 v189, v169
	v_mul_f32_e32 v184, v195, v195
	v_lshlrev_b32_e32 v148, 16, v149
	v_and_b32_e32 v149, 0xffff0000, v149
	v_pk_add_f32 v[172:173], v[172:173], v[188:189]
	v_pk_fma_f32 v[188:189], v[194:195], v[194:195], v[184:185] op_sel_hi:[1,1,0]
	v_mul_f32_e32 v184, v151, v151
	v_mul_f32_e32 v186, v148, v148
	v_mul_f32_e32 v198, v149, v149
	v_pk_fma_f32 v[192:193], v[150:151], v[150:151], v[184:185] op_sel_hi:[1,1,0]
	v_mov_b32_e32 v189, v186
	v_mov_b32_e32 v193, v198
	v_pk_add_f32 v[188:189], v[188:189], v[192:193]
	v_mov_b32_e32 v186, v185
	v_pk_add_f32 v[172:173], v[172:173], v[188:189]
	v_mov_b32_e32 v198, v197
	v_add_f32_e32 v169, v172, v173
	s_waitcnt lgkmcnt(0)
	s_nop 1
	v_add_f32_dpp v169, v169, v169 quad_perm:[1,0,3,2] row_mask:0xf bank_mask:0xf
	s_nop 1
	v_add_f32_dpp v169, v169, v169 quad_perm:[2,3,0,1] row_mask:0xf bank_mask:0xf
	s_nop 1
	v_add_f32_dpp v169, v169, v169 row_half_mirror row_mask:0xf bank_mask:0xf
	s_nop 1
	v_add_f32_dpp v169, v169, v169 row_mirror row_mask:0xf bank_mask:0xf
	v_mov_b32_e32 v172, v169
	s_nop 1
	v_permlane16_swap_b32_e32 v169, v172
	v_add_f32_e32 v169, v169, v172
	v_mov_b32_e32 v172, v169
	s_nop 1
	v_permlane32_swap_b32_e32 v169, v172
	v_add_f32_e32 v169, v169, v172
	v_fmamk_f32 v169, v169, 0x3a000000, v252
	v_mul_f32_e32 v172, 0x4b800000, v169
	v_cmp_gt_f32_e32 vcc, s88, v169
	s_nop 1
	v_cndmask_b32_e32 v169, v169, v172, vcc
	v_rsq_f32_e32 v169, v169
	s_nop 0
	v_mul_f32_e32 v172, 0x45800000, v169
	v_cndmask_b32_e32 v172, v169, v172, vcc
	v_pk_mul_f32 v[170:171], v[172:173], v[170:171] op_sel_hi:[0,1]
	v_pk_mul_f32 v[162:163], v[172:173], v[162:163] op_sel_hi:[0,1]
	s_waitcnt vmcnt(15)
	v_pk_mul_f32 v[92:93], v[92:93], v[170:171]
	v_pk_mul_f32 v[94:95], v[94:95], v[162:163]
	s_waitcnt vmcnt(13)
	v_pk_fma_f32 v[0:1], v[88:89], v[92:93], v[0:1]
	v_mov_b32_e32 v88, v175
	v_mov_b32_e32 v175, v160
	v_pk_fma_f32 v[2:3], v[90:91], v[94:95], v[2:3]
	v_mov_b32_e32 v89, v161
	v_pk_mul_f32 v[90:91], v[172:173], v[174:175] op_sel_hi:[0,1]
	v_pk_mul_f32 v[88:89], v[172:173], v[88:89] op_sel_hi:[0,1]
	v_pk_mul_f32 v[84:85], v[84:85], v[90:91]
	v_pk_mul_f32 v[86:87], v[86:87], v[88:89]
	s_waitcnt vmcnt(12)
	v_pk_fma_f32 v[4:5], v[80:81], v[84:85], v[4:5]
	v_pk_mul_f32 v[80:81], v[172:173], v[158:159] op_sel_hi:[0,1]
	v_pk_fma_f32 v[6:7], v[82:83], v[86:87], v[6:7]
	v_pk_mul_f32 v[82:83], v[172:173], v[182:183] op_sel_hi:[0,1]
	s_waitcnt vmcnt(11)
	v_pk_mul_f32 v[78:79], v[78:79], v[80:81]
	v_pk_mul_f32 v[76:77], v[76:77], v[82:83]
	s_waitcnt vmcnt(9)
	v_pk_fma_f32 v[10:11], v[74:75], v[78:79], v[10:11]
	v_pk_mul_f32 v[74:75], v[186:187], v[172:173] op_sel_hi:[1,0]
	v_pk_fma_f32 v[8:9], v[72:73], v[76:77], v[8:9]
	v_pk_mul_f32 v[72:73], v[156:157], v[172:173] op_sel_hi:[1,0]
	v_pk_mul_f32 v[68:69], v[68:69], v[74:75]
	v_pk_mul_f32 v[70:71], v[70:71], v[72:73]
	s_waitcnt vmcnt(8)
	v_pk_fma_f32 v[12:13], v[64:65], v[68:69], v[12:13]
	v_mov_b32_e32 v64, v181
	v_mov_b32_e32 v181, v154
	v_pk_fma_f32 v[14:15], v[66:67], v[70:71], v[14:15]
	v_pk_mul_f32 v[66:67], v[172:173], v[180:181] op_sel_hi:[0,1]
	s_waitcnt vmcnt(7)
	v_pk_mul_f32 v[60:61], v[60:61], v[66:67]
	v_mov_b32_e32 v65, v155
	s_waitcnt vmcnt(5)
	v_pk_fma_f32 v[16:17], v[56:57], v[60:61], v[16:17]
	v_mov_b32_e32 v56, v191
	v_mov_b32_e32 v57, v153
	v_pk_mul_f32 v[56:57], v[172:173], v[56:57] op_sel_hi:[0,1]
	v_pk_mul_f32 v[54:55], v[54:55], v[56:57]
	v_pk_mul_f32 v[64:65], v[172:173], v[64:65] op_sel_hi:[0,1]
	s_waitcnt vmcnt(4)
	v_pk_fma_f32 v[22:23], v[50:51], v[54:55], v[22:23]
	v_pk_mul_f32 v[50:51], v[172:173], v[194:195] op_sel_hi:[0,1]
	v_pk_mul_f32 v[62:63], v[62:63], v[64:65]
	v_mov_b32_e32 v191, v152
	s_waitcnt vmcnt(3)
	v_pk_mul_f32 v[44:45], v[44:45], v[50:51]
	v_pk_fma_f32 v[18:19], v[58:59], v[62:63], v[18:19]
	v_pk_mul_f32 v[58:59], v[172:173], v[190:191] op_sel_hi:[0,1]
	s_waitcnt vmcnt(1)
	v_pk_fma_f32 v[24:25], v[40:41], v[44:45], v[24:25]
	v_pk_mul_f32 v[40:41], v[148:149], v[172:173] op_sel_hi:[1,0]
	v_pk_mul_f32 v[52:53], v[52:53], v[58:59]
	v_pk_mul_f32 v[38:39], v[38:39], v[40:41]
	v_pk_fma_f32 v[20:21], v[48:49], v[52:53], v[20:21]
	v_pk_mul_f32 v[48:49], v[172:173], v[150:151] op_sel_hi:[0,1]
	s_waitcnt vmcnt(0)
	v_pk_fma_f32 v[30:31], v[34:35], v[38:39], v[30:31]
	v_pk_mul_f32 v[46:47], v[46:47], v[48:49]
	v_pk_fma_f32 v[26:27], v[42:43], v[46:47], v[26:27]
	v_pk_mul_f32 v[42:43], v[198:199], v[172:173] op_sel_hi:[1,0]
	v_pk_mul_f32 v[36:37], v[36:37], v[42:43]
	v_cvt_pk_bf16_f32 v34, v0, v1
	v_pk_fma_f32 v[28:29], v[32:33], v[36:37], v[28:29]
	v_lshl_add_u64 v[32:33], v[98:99], 0, s[12:13]
	v_cvt_pk_bf16_f32 v35, v2, v3
	global_store_dwordx2 v[32:33], v[34:35], off
	v_cvt_pk_bf16_f32 v34, v4, v5
	v_cvt_pk_bf16_f32 v35, v6, v7
	global_store_dwordx2 v[32:33], v[34:35], off offset:512
	v_cvt_pk_bf16_f32 v34, v8, v9
	v_cvt_pk_bf16_f32 v35, v10, v11
	global_store_dwordx2 v[32:33], v[34:35], off offset:1024
	v_cvt_pk_bf16_f32 v34, v12, v13
	v_cvt_pk_bf16_f32 v35, v14, v15
	global_store_dwordx2 v[32:33], v[34:35], off offset:1536
	v_cvt_pk_bf16_f32 v34, v16, v17
	v_cvt_pk_bf16_f32 v35, v18, v19
	global_store_dwordx2 v[32:33], v[34:35], off offset:2048
	v_cvt_pk_bf16_f32 v34, v20, v21
	v_cvt_pk_bf16_f32 v35, v22, v23
	global_store_dwordx2 v[32:33], v[34:35], off offset:2560
	v_cvt_pk_bf16_f32 v34, v24, v25
	v_cvt_pk_bf16_f32 v35, v26, v27
	global_store_dwordx2 v[32:33], v[34:35], off offset:3072
	v_cvt_pk_bf16_f32 v34, v28, v29
	v_cvt_pk_bf16_f32 v35, v30, v31
	global_store_dwordx2 v[32:33], v[34:35], off offset:3584
	v_mad_i64_i32 v[32:33], s[16:17], s14, v224, v[126:127]
	v_mad_i64_i32 v[34:35], s[14:15], s14, v224, v[130:131]
	s_movk_i32 s14, 0x1000
	global_load_dwordx4 v[68:71], v[102:103], off
	global_load_dwordx4 v[72:75], v[102:103], off offset:1024
	global_load_dwordx4 v[76:79], v[32:33], off
	global_load_dwordx4 v[80:83], v[32:33], off offset:1024
	global_load_dwordx4 v[84:87], v[34:35], off
	global_load_dwordx4 v[88:91], v[34:35], off offset:1024
	global_load_dwordx4 v[92:95], v[102:103], off offset:2048
	global_load_dwordx4 v[148:151], v[102:103], off offset:3072
	global_load_dwordx4 v[152:155], v[32:33], off offset:2048
	global_load_dwordx4 v[156:159], v[32:33], off offset:3072
	global_load_dwordx4 v[160:163], v[34:35], off offset:2048
	global_load_dwordx4 v[170:173], v[34:35], off offset:3072
	v_add_co_u32_e32 v32, vcc, s14, v32
	s_nop 1
	v_addc_co_u32_e32 v33, vcc, 0, v33, vcc
	v_add_co_u32_e32 v34, vcc, s14, v34
	s_nop 1
	v_addc_co_u32_e32 v35, vcc, 0, v35, vcc
	global_load_dwordx4 v[180:183], v[114:115], off
	global_load_dwordx4 v[64:67], v[116:117], off
	global_load_dwordx4 v[184:187], v[32:33], off
	global_load_dwordx4 v[60:63], v[32:33], off offset:1024
	global_load_dwordx4 v[188:191], v[34:35], off
	global_load_dwordx4 v[56:59], v[34:35], off offset:1024
	global_load_dwordx4 v[48:51], v[118:119], off
	global_load_dwordx4 v[40:43], v[120:121], off
	global_load_dwordx4 v[52:55], v[32:33], off offset:2048
	global_load_dwordx4 v[36:39], v[32:33], off offset:3072
	global_load_dwordx4 v[44:47], v[34:35], off offset:2048
	s_nop 0
	global_load_dwordx4 v[32:35], v[34:35], off offset:3072
	v_mov_b32_e32 v192, v1
	v_mov_b32_e32 v193, v5
	v_mov_b32_e32 v174, v0
	v_mov_b32_e32 v175, v4
	v_pk_mul_f32 v[192:193], v[192:193], v[192:193]
	v_mov_b32_e32 v194, v3
	v_mov_b32_e32 v195, v7
	v_pk_fma_f32 v[174:175], v[174:175], v[174:175], v[192:193]
	v_mov_b32_e32 v192, v2
	v_mov_b32_e32 v193, v6
	v_pk_mul_f32 v[194:195], v[194:195], v[194:195]
	s_waitcnt vmcnt(21)
	v_pk_add_f32 v[76:77], v[76:77], 1.0 op_sel_hi:[1,0]
	v_pk_fma_f32 v[192:193], v[192:193], v[192:193], v[194:195]
	v_pk_mul_f32 v[194:195], v[8:9], v[8:9]
	v_pk_add_f32 v[174:175], v[174:175], v[192:193]
	v_pk_mul_f32 v[192:193], v[10:11], v[10:11]
	v_pk_add_f32 v[174:175], v[174:175], v[174:175] op_sel_hi:[0,1]
	v_pk_mov_b32 v[196:197], v[194:195], v[192:193] op_sel:[1,0]
	v_mov_b32_e32 v195, v193
	v_mul_f32_e32 v174, v12, v12
	v_pk_add_f32 v[192:193], v[196:197], v[194:195]
	v_pk_fma_f32 v[194:195], v[12:13], v[12:13], v[174:175] op_sel_hi:[1,1,0]
	v_mul_f32_e32 v174, v14, v14
	v_pk_add_f32 v[192:193], v[192:193], v[192:193] op_sel_hi:[0,1]
	v_pk_fma_f32 v[196:197], v[14:15], v[14:15], v[174:175] op_sel_hi:[1,1,0]
	v_mul_f32_e32 v194, v16, v16
	v_mul_f32_e32 v196, v17, v17
	v_mul_f32_e32 v192, v18, v18
	v_mul_f32_e32 v174, v19, v19
	v_pk_add_f32 v[194:195], v[194:195], v[196:197]
	v_pk_add_f32 v[174:175], v[192:193], v[174:175]
	v_pk_mul_f32 v[192:193], v[22:23], v[22:23]
	v_pk_add_f32 v[174:175], v[194:195], v[174:175]
	v_pk_mul_f32 v[194:195], v[20:21], v[20:21]
	v_pk_add_f32 v[174:175], v[174:175], v[174:175] op_sel_hi:[0,1]
	v_pk_mov_b32 v[196:197], v[194:195], v[192:193] op_sel:[1,0]
	v_mov_b32_e32 v195, v193
	v_mul_f32_e32 v174, v24, v24
	v_pk_add_f32 v[192:193], v[196:197], v[194:195]
	v_pk_fma_f32 v[194:195], v[24:25], v[24:25], v[174:175] op_sel_hi:[1,1,0]
	v_mul_f32_e32 v174, v26, v26
	v_pk_add_f32 v[192:193], v[192:193], v[192:193] op_sel_hi:[0,1]
	v_pk_fma_f32 v[196:197], v[26:27], v[26:27], v[174:175] op_sel_hi:[1,1,0]
	v_mul_f32_e32 v194, v28, v28
	v_mul_f32_e32 v196, v29, v29
	v_mul_f32_e32 v192, v30, v30
	v_mul_f32_e32 v174, v31, v31
	v_pk_add_f32 v[194:195], v[194:195], v[196:197]
	v_pk_add_f32 v[174:175], v[192:193], v[174:175]
	v_pk_add_f32 v[78:79], v[78:79], 1.0 op_sel_hi:[1,0]
	v_pk_add_f32 v[174:175], v[194:195], v[174:175]
	v_lshl_add_u64 v[192:193], v[104:105], 0, s[12:13]
	v_add_f32_e32 v169, v174, v175
	s_waitcnt vmcnt(8)
	v_pk_add_f32 v[60:61], v[60:61], 1.0 op_sel_hi:[1,0]
	v_pk_add_f32 v[62:63], v[62:63], 1.0 op_sel_hi:[1,0]
	s_waitcnt vmcnt(3)
	v_pk_add_f32 v[52:53], v[52:53], 1.0 op_sel_hi:[1,0]
	v_pk_add_f32 v[54:55], v[54:55], 1.0 op_sel_hi:[1,0]
	s_waitcnt lgkmcnt(0)
	s_waitcnt vmcnt(2)
	v_pk_add_f32 v[36:37], v[36:37], 1.0 op_sel_hi:[1,0]
	v_pk_add_f32 v[38:39], v[38:39], 1.0 op_sel_hi:[1,0]
	v_readlane_b32 s12, v254, 11
	v_readlane_b32 s13, v254, 12
	s_add_u32 s24, s24, s12
	s_addc_u32 s25, s25, s13
	v_readlane_b32 s12, v254, 9
	v_readlane_b32 s13, v254, 10
	s_add_u32 s10, s10, s12
	s_addc_u32 s11, s11, s13
	s_cmpk_gt_i32 s24, 0x3fff
	s_nop 1
	v_add_f32_dpp v169, v169, v169 quad_perm:[1,0,3,2] row_mask:0xf bank_mask:0xf
	s_nop 1
	v_add_f32_dpp v169, v169, v169 quad_perm:[2,3,0,1] row_mask:0xf bank_mask:0xf
	s_nop 1
	v_add_f32_dpp v169, v169, v169 row_half_mirror row_mask:0xf bank_mask:0xf
	s_nop 1
	v_add_f32_dpp v169, v169, v169 row_mirror row_mask:0xf bank_mask:0xf
	v_mov_b32_e32 v174, v169
	s_nop 1
	v_permlane16_swap_b32_e32 v169, v174
	v_add_f32_e32 v169, v169, v174
	v_mov_b32_e32 v174, v169
	s_nop 1
	v_permlane32_swap_b32_e32 v169, v174
	v_add_f32_e32 v169, v169, v174
	v_fmamk_f32 v169, v169, 0x3a000000, v252
	v_mul_f32_e32 v174, 0x4b800000, v169
	v_cmp_gt_f32_e32 vcc, s88, v169
	s_nop 1
	v_cndmask_b32_e32 v169, v169, v174, vcc
	v_rsq_f32_e32 v169, v169
	s_nop 0
	v_mul_f32_e32 v174, 0x45800000, v169
	v_cndmask_b32_e32 v174, v169, v174, vcc
	v_pk_mul_f32 v[196:197], v[0:1], v[174:175] op_sel_hi:[1,0]
	v_pk_mul_f32 v[194:195], v[2:3], v[174:175] op_sel_hi:[1,0]
	v_pk_mul_f32 v[68:69], v[68:69], v[196:197]
	v_pk_mul_f32 v[70:71], v[70:71], v[194:195]
	v_pk_fma_f32 v[68:69], v[76:77], v[68:69], v[84:85]
	v_pk_fma_f32 v[70:71], v[78:79], v[70:71], v[86:87]
	v_cvt_pk_bf16_f32 v68, v68, v69
	v_cvt_pk_bf16_f32 v69, v70, v71
	global_store_dwordx2 v[192:193], v[68:69], off
	v_pk_mul_f32 v[68:69], v[6:7], v[174:175] op_sel_hi:[1,0]
	v_pk_mul_f32 v[70:71], v[4:5], v[174:175] op_sel_hi:[1,0]
	v_pk_mul_f32 v[68:69], v[74:75], v[68:69]
	v_pk_mul_f32 v[70:71], v[72:73], v[70:71]
	v_pk_add_f32 v[74:75], v[80:81], 1.0 op_sel_hi:[1,0]
	v_pk_add_f32 v[72:73], v[82:83], 1.0 op_sel_hi:[1,0]
	v_pk_fma_f32 v[70:71], v[74:75], v[70:71], v[88:89]
	v_pk_fma_f32 v[68:69], v[72:73], v[68:69], v[90:91]
	v_cvt_pk_bf16_f32 v70, v70, v71
	v_cvt_pk_bf16_f32 v71, v68, v69
	global_store_dwordx2 v[192:193], v[70:71], off offset:512
	v_pk_mul_f32 v[70:71], v[8:9], v[174:175] op_sel_hi:[1,0]
	v_pk_mul_f32 v[68:69], v[10:11], v[174:175] op_sel_hi:[1,0]
	v_pk_mul_f32 v[70:71], v[92:93], v[70:71]
	v_pk_add_f32 v[74:75], v[152:153], 1.0 op_sel_hi:[1,0]
	v_pk_mul_f32 v[68:69], v[94:95], v[68:69]
	v_pk_add_f32 v[72:73], v[154:155], 1.0 op_sel_hi:[1,0]
	v_pk_fma_f32 v[70:71], v[74:75], v[70:71], v[160:161]
	v_pk_fma_f32 v[68:69], v[72:73], v[68:69], v[162:163]
	v_cvt_pk_bf16_f32 v70, v70, v71
	v_cvt_pk_bf16_f32 v71, v68, v69
	global_store_dwordx2 v[192:193], v[70:71], off offset:1024
	v_pk_mul_f32 v[70:71], v[12:13], v[174:175] op_sel_hi:[1,0]
	v_pk_mul_f32 v[68:69], v[14:15], v[174:175] op_sel_hi:[1,0]
	v_pk_mul_f32 v[70:71], v[148:149], v[70:71]
	v_pk_add_f32 v[74:75], v[156:157], 1.0 op_sel_hi:[1,0]
	v_pk_mul_f32 v[68:69], v[150:151], v[68:69]
	v_pk_add_f32 v[72:73], v[158:159], 1.0 op_sel_hi:[1,0]
	v_pk_fma_f32 v[70:71], v[74:75], v[70:71], v[170:171]
	v_pk_fma_f32 v[68:69], v[72:73], v[68:69], v[172:173]
	v_cvt_pk_bf16_f32 v70, v70, v71
	v_cvt_pk_bf16_f32 v71, v68, v69
	global_store_dwordx2 v[192:193], v[70:71], off offset:1536
	v_pk_mul_f32 v[70:71], v[16:17], v[174:175] op_sel_hi:[1,0]
	v_pk_mul_f32 v[68:69], v[18:19], v[174:175] op_sel_hi:[1,0]
	v_pk_mul_f32 v[70:71], v[180:181], v[70:71]
	v_pk_add_f32 v[74:75], v[184:185], 1.0 op_sel_hi:[1,0]
	v_pk_mul_f32 v[68:69], v[182:183], v[68:69]
	v_pk_add_f32 v[72:73], v[186:187], 1.0 op_sel_hi:[1,0]
	v_pk_fma_f32 v[70:71], v[74:75], v[70:71], v[188:189]
	v_pk_fma_f32 v[68:69], v[72:73], v[68:69], v[190:191]
	v_cvt_pk_bf16_f32 v70, v70, v71
	v_cvt_pk_bf16_f32 v71, v68, v69
	global_store_dwordx2 v[192:193], v[70:71], off offset:2048
	v_pk_mul_f32 v[70:71], v[20:21], v[174:175] op_sel_hi:[1,0]
	v_pk_mul_f32 v[68:69], v[22:23], v[174:175] op_sel_hi:[1,0]
	v_pk_mul_f32 v[64:65], v[64:65], v[70:71]
	v_pk_mul_f32 v[66:67], v[66:67], v[68:69]
	v_pk_fma_f32 v[56:57], v[60:61], v[64:65], v[56:57]
	v_pk_fma_f32 v[58:59], v[62:63], v[66:67], v[58:59]
	v_cvt_pk_bf16_f32 v56, v56, v57
	v_cvt_pk_bf16_f32 v57, v58, v59
	v_pk_mul_f32 v[58:59], v[24:25], v[174:175] op_sel_hi:[1,0]
	global_store_dwordx2 v[192:193], v[56:57], off offset:2560
	v_pk_mul_f32 v[48:49], v[48:49], v[58:59]
	v_pk_mul_f32 v[56:57], v[26:27], v[174:175] op_sel_hi:[1,0]
	s_waitcnt vmcnt(7)
	v_pk_fma_f32 v[44:45], v[52:53], v[48:49], v[44:45]
	v_pk_mul_f32 v[50:51], v[50:51], v[56:57]
	v_pk_fma_f32 v[46:47], v[54:55], v[50:51], v[46:47]
	v_cvt_pk_bf16_f32 v44, v44, v45
	v_cvt_pk_bf16_f32 v45, v46, v47
	v_pk_mul_f32 v[46:47], v[28:29], v[174:175] op_sel_hi:[1,0]
	global_store_dwordx2 v[192:193], v[44:45], off offset:3072
	v_pk_mul_f32 v[40:41], v[40:41], v[46:47]
	v_pk_mul_f32 v[44:45], v[30:31], v[174:175] op_sel_hi:[1,0]
	s_waitcnt vmcnt(7)
	v_pk_fma_f32 v[32:33], v[36:37], v[40:41], v[32:33]
	v_pk_mul_f32 v[42:43], v[42:43], v[44:45]
	v_pk_fma_f32 v[34:35], v[38:39], v[42:43], v[34:35]
	v_cvt_pk_bf16_f32 v32, v32, v33
	v_cvt_pk_bf16_f32 v33, v34, v35
	global_store_dwordx2 v[192:193], v[32:33], off offset:3584
	v_mov_b64_e32 v[32:33], v[146:147]
	v_mov_b64_e32 v[34:35], v[144:145]
	v_mov_b64_e32 v[36:37], v[142:143]
	v_mov_b64_e32 v[38:39], v[140:141]
	v_mov_b64_e32 v[40:41], v[138:139]
	v_mov_b64_e32 v[42:43], v[136:137]
	v_mov_b64_e32 v[44:45], v[134:135]
	v_mov_b64_e32 v[46:47], v[132:133]
	s_cbranch_scc1 .LBB0_939

.LBB0_1206:
	v_lshl_add_u64 v[164:165], s[0:1], 0, v[178:179]
	v_add_co_u32_e32 v96, vcc, 0x4b400000, v164
	v_lshl_add_u64 v[112:113], s[2:3], 0, v[178:179]
	s_nop 0
	v_addc_co_u32_e32 v97, vcc, 0, v165, vcc
	v_add_co_u32_e32 v112, vcc, 0x31200000, v112
	global_load_dwordx2 v[98:99], v[96:97], off
	global_load_dwordx2 v[100:101], v[96:97], off offset:512
	global_load_dwordx2 v[102:103], v[96:97], off offset:1024
	global_load_dwordx2 v[104:105], v[96:97], off offset:1536
	global_load_dwordx2 v[106:107], v[96:97], off offset:2048
	global_load_dwordx2 v[108:109], v[96:97], off offset:2560
	global_load_dwordx2 v[110:111], v[96:97], off offset:3072
	s_nop 0
	global_load_dwordx2 v[96:97], v[96:97], off offset:3584
	v_addc_co_u32_e32 v113, vcc, 0, v113, vcc
	global_load_dwordx2 v[114:115], v[112:113], off
	global_load_dwordx2 v[116:117], v[112:113], off offset:512
	global_load_dwordx2 v[118:119], v[112:113], off offset:1024
	global_load_dwordx2 v[120:121], v[112:113], off offset:1536
	global_load_dwordx2 v[122:123], v[112:113], off offset:2048
	global_load_dwordx2 v[124:125], v[112:113], off offset:2560
	global_load_dwordx2 v[126:127], v[112:113], off offset:3072
	s_nop 0
	global_load_dwordx2 v[112:113], v[112:113], off offset:3584
	s_waitcnt vmcnt(0)
	v_lshlrev_b32_e32 v180, 16, v114
	v_and_b32_e32 v181, 0xffff0000, v114
	v_lshlrev_b32_e32 v114, 16, v115
	v_and_b32_e32 v115, 0xffff0000, v115
	v_mul_f32_e32 v182, v115, v115
	v_lshlrev_b32_e32 v191, 16, v120
	v_and_b32_e32 v193, 0xffff0000, v120
	v_mul_f32_e32 v120, v181, v181
	v_pk_fma_f32 v[182:183], v[114:115], v[114:115], v[182:183] op_sel_hi:[1,1,0]
	v_lshlrev_b32_e32 v185, 16, v117
	v_lshlrev_b32_e32 v184, 16, v116
	v_and_b32_e32 v117, 0xffff0000, v117
	v_and_b32_e32 v116, 0xffff0000, v116
	v_lshlrev_b32_e32 v194, 16, v121
	v_and_b32_e32 v195, 0xffff0000, v121
	v_pk_fma_f32 v[120:121], v[180:181], v[180:181], v[120:121] op_sel_hi:[1,1,0]
	v_pk_mul_f32 v[186:187], v[116:117], v[116:117]
	v_mov_b32_e32 v190, v120
	v_mov_b32_e32 v196, v182
	v_mov_b32_e32 v197, v191
	v_pk_fma_f32 v[186:187], v[184:185], v[184:185], v[186:187]
	v_pk_add_f32 v[120:121], v[120:121], v[182:183]
	v_pk_mul_f32 v[182:183], v[190:191], v[196:197]
	v_mul_f32_e32 v171, v193, v193
	v_mov_b32_e32 v121, v183
	v_pk_add_f32 v[182:183], v[186:187], v[186:187] op_sel:[0,1] op_sel_hi:[1,0]
	v_lshlrev_b32_e32 v188, 16, v118
	v_and_b32_e32 v189, 0xffff0000, v118
	v_lshlrev_b32_e32 v118, 16, v119
	v_and_b32_e32 v119, 0xffff0000, v119
	v_mov_b32_e32 v183, v171
	v_pk_add_f32 v[120:121], v[120:121], v[182:183]
	v_mul_f32_e32 v182, v189, v189
	v_mul_f32_e32 v186, v119, v119
	v_mul_f32_e32 v175, v194, v194
	v_mul_f32_e32 v192, v195, v195
	v_pk_fma_f32 v[182:183], v[188:189], v[188:189], v[182:183] op_sel_hi:[1,1,0]
	v_pk_fma_f32 v[186:187], v[118:119], v[118:119], v[186:187] op_sel_hi:[1,1,0]
	v_mov_b32_e32 v183, v175
	v_mov_b32_e32 v187, v192
	v_pk_add_f32 v[182:183], v[182:183], v[186:187]
	v_and_b32_e32 v187, 0xffff0000, v123
	v_and_b32_e32 v186, 0xffff0000, v122
	v_pk_add_f32 v[120:121], v[120:121], v[182:183]
	v_lshlrev_b32_e32 v183, 16, v123
	v_lshlrev_b32_e32 v182, 16, v122
	v_pk_mul_f32 v[122:123], v[186:187], v[186:187]
	v_and_b32_e32 v199, 0xffff0000, v125
	v_pk_fma_f32 v[122:123], v[182:183], v[182:183], v[122:123]
	v_and_b32_e32 v198, 0xffff0000, v124
	v_pk_add_f32 v[122:123], v[122:123], v[122:123] op_sel:[0,1] op_sel_hi:[1,0]
	v_lshlrev_b32_e32 v205, 16, v112
	v_and_b32_e32 v207, 0xffff0000, v112
	v_lshlrev_b32_e32 v208, 16, v113
	v_and_b32_e32 v209, 0xffff0000, v113
	v_pk_add_f32 v[112:113], v[120:121], v[120:121] op_sel:[0,1] op_sel_hi:[1,0]
	v_lshlrev_b32_e32 v197, 16, v125
	v_lshlrev_b32_e32 v196, 16, v124
	v_pk_mul_f32 v[124:125], v[198:199], v[198:199]
	v_mov_b32_e32 v204, v112
	v_mov_b32_e32 v120, v122
	v_mov_b32_e32 v121, v205
	v_pk_fma_f32 v[124:125], v[196:197], v[196:197], v[124:125]
	v_pk_add_f32 v[112:113], v[112:113], v[122:123]
	v_pk_mul_f32 v[120:121], v[204:205], v[120:121]
	v_lshlrev_b32_e32 v200, 16, v126
	v_and_b32_e32 v201, 0xffff0000, v126
	v_mul_f32_e32 v126, v207, v207
	v_mov_b32_e32 v113, v121
	v_pk_add_f32 v[120:121], v[124:125], v[124:125] op_sel:[0,1] op_sel_hi:[1,0]
	v_and_b32_e32 v203, 0xffff0000, v127
	v_mov_b32_e32 v121, v126
	v_lshlrev_b32_e32 v202, 16, v127
	v_pk_add_f32 v[112:113], v[112:113], v[120:121]
	v_mul_f32_e32 v120, v201, v201
	v_mul_f32_e32 v122, v203, v203
	v_mul_f32_e32 v127, v208, v208
	v_mul_f32_e32 v171, v209, v209
	v_pk_fma_f32 v[120:121], v[200:201], v[200:201], v[120:121] op_sel_hi:[1,1,0]
	v_pk_fma_f32 v[122:123], v[202:203], v[202:203], v[122:123] op_sel_hi:[1,1,0]
	v_mov_b32_e32 v121, v127
	v_mov_b32_e32 v123, v171
	v_pk_add_f32 v[120:121], v[120:121], v[122:123]
	v_lshlrev_b32_e32 v226, 16, v108
	v_pk_add_f32 v[112:113], v[112:113], v[120:121]
	v_and_b32_e32 v227, 0xffff0000, v108
	v_add_f32_e32 v113, v112, v113
	v_lshlrev_b32_e32 v228, 16, v109
	v_and_b32_e32 v229, 0xffff0000, v109
	v_lshlrev_b32_e32 v172, 16, v98
	v_and_b32_e32 v173, 0xffff0000, v98
	s_waitcnt lgkmcnt(0)
	s_nop 1
	v_add_f32_dpp v120, v113, v113 quad_perm:[1,0,3,2] row_mask:0xf bank_mask:0xf
	s_nop 1
	v_add_f32_dpp v120, v120, v120 quad_perm:[2,3,0,1] row_mask:0xf bank_mask:0xf
	s_nop 1
	v_add_f32_dpp v120, v120, v120 row_half_mirror row_mask:0xf bank_mask:0xf
	s_nop 1
	v_add_f32_dpp v120, v120, v120 row_mirror row_mask:0xf bank_mask:0xf
	v_mov_b32_e32 v121, v120
	s_nop 1
	v_permlane16_swap_b32_e32 v120, v121
	v_add_f32_e32 v120, v120, v121
	v_mov_b32_e32 v121, v120
	s_nop 1
	v_permlane32_swap_b32_e32 v120, v121
	v_add_f32_e32 v120, v120, v121
	v_lshlrev_b32_e32 v98, 16, v99
	v_and_b32_e32 v99, 0xffff0000, v99
	v_lshlrev_b32_e32 v174, 16, v100
	v_and_b32_e32 v175, 0xffff0000, v100
	v_lshlrev_b32_e32 v100, 16, v101
	v_and_b32_e32 v101, 0xffff0000, v101
	v_lshlrev_b32_e32 v112, 16, v102
	v_and_b32_e32 v113, 0xffff0000, v102
	v_lshlrev_b32_e32 v102, 16, v103
	v_and_b32_e32 v103, 0xffff0000, v103
	v_lshlrev_b32_e32 v210, 16, v104
	v_and_b32_e32 v211, 0xffff0000, v104
	v_lshlrev_b32_e32 v104, 16, v105
	v_and_b32_e32 v105, 0xffff0000, v105
	v_lshlrev_b32_e32 v230, 16, v110
	v_and_b32_e32 v231, 0xffff0000, v110
	v_lshlrev_b32_e32 v232, 16, v111
	v_and_b32_e32 v233, 0xffff0000, v111
	v_mov_b32_e32 v192, v191
	v_lshlrev_b32_e32 v212, 16, v106
	v_mov_b32_e32 v108, v120
	v_fmamk_f32 v108, v108, 0x3a000000, v252
	v_mul_f32_e32 v109, 0x4b800000, v108
	v_cmp_gt_f32_e32 vcc, s88, v108
	v_and_b32_e32 v213, 0xffff0000, v106
	v_lshlrev_b32_e32 v106, 16, v107
	v_cndmask_b32_e32 v108, v108, v109, vcc
	v_rsq_f32_e32 v108, v108
	v_and_b32_e32 v107, 0xffff0000, v107
	v_mov_b32_e32 v206, v205
	v_lshlrev_b32_e32 v234, 16, v96
	v_mul_f32_e32 v109, 0x45800000, v108
	v_cndmask_b32_e32 v190, v108, v109, vcc
	v_pk_mul_f32 v[108:109], v[190:191], v[114:115] op_sel_hi:[0,1]
	v_pk_mul_f32 v[108:109], v[2:3], v[108:109]
	v_pk_mul_f32 v[110:111], v[190:191], v[180:181] op_sel_hi:[0,1]
	v_pk_fma_f32 v[126:127], v[10:11], v[108:109], v[98:99]
	v_mov_b32_e32 v98, v185
	v_mov_b32_e32 v99, v117
	v_pk_mul_f32 v[98:99], v[190:191], v[98:99] op_sel_hi:[0,1]
	v_pk_mul_f32 v[98:99], v[6:7], v[98:99]
	v_pk_mul_f32 v[110:111], v[0:1], v[110:111]
	v_pk_fma_f32 v[122:123], v[14:15], v[98:99], v[100:101]
	v_pk_mul_f32 v[98:99], v[190:191], v[118:119] op_sel_hi:[0,1]
	v_pk_mul_f32 v[98:99], v[18:19], v[98:99]
	v_pk_mul_f32 v[100:101], v[190:191], v[188:189] op_sel_hi:[0,1]
	v_pk_fma_f32 v[118:119], v[26:27], v[98:99], v[102:103]
	v_pk_mul_f32 v[98:99], v[194:195], v[190:191] op_sel_hi:[1,0]
	v_pk_mul_f32 v[100:101], v[16:17], v[100:101]
	v_pk_mul_f32 v[98:99], v[22:23], v[98:99]
	v_mov_b32_e32 v185, v116
	v_pk_fma_f32 v[114:115], v[30:31], v[98:99], v[104:105]
	v_mov_b32_e32 v98, v183
	v_mov_b32_e32 v99, v187
	v_pk_mul_f32 v[98:99], v[190:191], v[98:99] op_sel_hi:[0,1]
	v_pk_fma_f32 v[116:117], v[24:25], v[100:101], v[112:113]
	v_pk_mul_f32 v[100:101], v[192:193], v[190:191] op_sel_hi:[1,0]
	v_pk_mul_f32 v[98:99], v[34:35], v[98:99]
	v_pk_fma_f32 v[124:125], v[8:9], v[110:111], v[172:173]
	v_pk_mul_f32 v[100:101], v[20:21], v[100:101]
	v_mov_b32_e32 v183, v186
	v_pk_fma_f32 v[110:111], v[42:43], v[98:99], v[106:107]
	v_mov_b32_e32 v98, v197
	v_mov_b32_e32 v99, v199
	v_pk_mul_f32 v[108:109], v[190:191], v[184:185] op_sel_hi:[0,1]
	v_pk_fma_f32 v[112:113], v[28:29], v[100:101], v[210:211]
	v_pk_mul_f32 v[100:101], v[190:191], v[182:183] op_sel_hi:[0,1]
	v_pk_mul_f32 v[98:99], v[190:191], v[98:99] op_sel_hi:[0,1]
	v_pk_mul_f32 v[108:109], v[4:5], v[108:109]
	v_pk_mul_f32 v[100:101], v[32:33], v[100:101]
	v_mov_b32_e32 v197, v198
	v_pk_mul_f32 v[98:99], v[38:39], v[98:99]
	v_pk_fma_f32 v[120:121], v[12:13], v[108:109], v[174:175]
	v_pk_fma_f32 v[108:109], v[40:41], v[100:101], v[212:213]
	v_pk_mul_f32 v[100:101], v[190:191], v[196:197] op_sel_hi:[0,1]
	v_pk_fma_f32 v[106:107], v[46:47], v[98:99], v[228:229]
	v_pk_mul_f32 v[98:99], v[190:191], v[202:203] op_sel_hi:[0,1]
	v_pk_mul_f32 v[100:101], v[36:37], v[100:101]
	v_pk_mul_f32 v[98:99], v[50:51], v[98:99]
	v_pk_fma_f32 v[104:105], v[44:45], v[100:101], v[226:227]
	v_pk_mul_f32 v[100:101], v[190:191], v[200:201] op_sel_hi:[0,1]
	v_pk_fma_f32 v[102:103], v[58:59], v[98:99], v[232:233]
	v_pk_mul_f32 v[98:99], v[208:209], v[190:191] op_sel_hi:[1,0]
	v_pk_mul_f32 v[172:173], v[206:207], v[190:191] op_sel_hi:[1,0]
	v_and_b32_e32 v235, 0xffff0000, v96
	v_lshlrev_b32_e32 v96, 16, v97
	v_and_b32_e32 v97, 0xffff0000, v97
	v_pk_mul_f32 v[100:101], v[48:49], v[100:101]
	v_pk_mul_f32 v[172:173], v[52:53], v[172:173]
	v_pk_mul_f32 v[98:99], v[54:55], v[98:99]
	v_pk_fma_f32 v[100:101], v[56:57], v[100:101], v[230:231]
	v_pk_fma_f32 v[98:99], v[62:63], v[98:99], v[96:97]
	v_pk_fma_f32 v[96:97], v[60:61], v[172:173], v[234:235]
	s_mov_b64 s[24:25], -1
	s_and_b64 vcc, exec, s[4:5]
	s_cbranch_vccnz .LBB0_1209
	s_andn2_b64 vcc, exec, s[24:25]
	s_cbranch_vccz .LBB0_1210

.LBB0_1211:
	v_mov_b32_e32 v174, v125
	v_mov_b32_e32 v175, v121
	v_mov_b32_e32 v172, v124
	v_mov_b32_e32 v173, v120
	v_pk_mul_f32 v[174:175], v[174:175], v[174:175]
	v_mov_b32_e32 v180, v127
	v_mov_b32_e32 v181, v123
	v_pk_fma_f32 v[172:173], v[172:173], v[172:173], v[174:175]
	v_mov_b32_e32 v174, v126
	v_mov_b32_e32 v175, v122
	v_pk_mul_f32 v[180:181], v[180:181], v[180:181]
	s_mov_b32 s24, 0x17800000
	v_pk_fma_f32 v[174:175], v[174:175], v[174:175], v[180:181]
	v_pk_mul_f32 v[180:181], v[116:117], v[116:117]
	v_pk_add_f32 v[172:173], v[172:173], v[174:175]
	v_pk_mul_f32 v[174:175], v[118:119], v[118:119]
	v_pk_add_f32 v[172:173], v[172:173], v[172:173] op_sel_hi:[0,1]
	v_pk_mov_b32 v[182:183], v[180:181], v[174:175] op_sel:[1,0]
	v_mov_b32_e32 v181, v175
	v_mul_f32_e32 v172, v112, v112
	v_pk_add_f32 v[174:175], v[182:183], v[180:181]
	v_pk_fma_f32 v[180:181], v[112:113], v[112:113], v[172:173] op_sel_hi:[1,1,0]
	v_mul_f32_e32 v172, v114, v114
	v_pk_add_f32 v[174:175], v[174:175], v[174:175] op_sel_hi:[0,1]
	v_pk_fma_f32 v[182:183], v[114:115], v[114:115], v[172:173] op_sel_hi:[1,1,0]
	v_mul_f32_e32 v180, v108, v108
	v_mul_f32_e32 v182, v109, v109
	v_mul_f32_e32 v174, v110, v110
	v_mul_f32_e32 v172, v111, v111
	v_pk_add_f32 v[180:181], v[180:181], v[182:183]
	v_pk_add_f32 v[172:173], v[174:175], v[172:173]
	v_pk_mul_f32 v[174:175], v[106:107], v[106:107]
	v_pk_add_f32 v[172:173], v[180:181], v[172:173]
	v_pk_mul_f32 v[180:181], v[104:105], v[104:105]
	v_pk_add_f32 v[172:173], v[172:173], v[172:173] op_sel_hi:[0,1]
	v_pk_mov_b32 v[182:183], v[180:181], v[174:175] op_sel:[1,0]
	v_mov_b32_e32 v181, v175
	v_mul_f32_e32 v172, v100, v100
	v_pk_add_f32 v[174:175], v[182:183], v[180:181]
	v_pk_fma_f32 v[180:181], v[100:101], v[100:101], v[172:173] op_sel_hi:[1,1,0]
	v_mul_f32_e32 v172, v102, v102
	v_pk_add_f32 v[174:175], v[174:175], v[174:175] op_sel_hi:[0,1]
	v_pk_fma_f32 v[182:183], v[102:103], v[102:103], v[172:173] op_sel_hi:[1,1,0]
	v_mul_f32_e32 v180, v96, v96
	v_mul_f32_e32 v182, v97, v97
	v_mul_f32_e32 v174, v98, v98
	v_mul_f32_e32 v172, v99, v99
	v_pk_add_f32 v[180:181], v[180:181], v[182:183]
	v_pk_add_f32 v[172:173], v[174:175], v[172:173]
	s_nop 0
	v_pk_add_f32 v[172:173], v[180:181], v[172:173]
	s_nop 0
	v_add_f32_e32 v171, v172, v173
	s_waitcnt lgkmcnt(0)
	s_nop 1
	v_add_f32_dpp v171, v171, v171 quad_perm:[1,0,3,2] row_mask:0xf bank_mask:0xf
	s_nop 1
	v_add_f32_dpp v171, v171, v171 quad_perm:[2,3,0,1] row_mask:0xf bank_mask:0xf
	s_nop 1
	v_add_f32_dpp v171, v171, v171 row_half_mirror row_mask:0xf bank_mask:0xf
	s_nop 1
	v_add_f32_dpp v171, v171, v171 row_mirror row_mask:0xf bank_mask:0xf
	v_mov_b32_e32 v172, v171
	s_nop 1
	v_permlane16_swap_b32_e32 v171, v172
	v_add_f32_e32 v171, v171, v172
	v_mov_b32_e32 v172, v171
	s_nop 1
	v_permlane32_swap_b32_e32 v171, v172
	v_add_f32_e32 v171, v171, v172
	v_fmamk_f32 v171, v171, 0x3a000000, v252
	v_mul_f32_e32 v172, 0x4b800000, v171
	v_cmp_gt_f32_e32 vcc, s88, v171
	s_nop 1
	v_cndmask_b32_e32 v171, v171, v172, vcc
	v_rsq_f32_e32 v171, v171
	s_nop 0
	v_mul_f32_e32 v172, 0x45800000, v171
	v_cndmask_b32_e32 v172, v171, v172, vcc
	v_pk_mul_f32 v[124:125], v[124:125], v[172:173] op_sel_hi:[1,0]
	v_pk_mul_f32 v[126:127], v[126:127], v[172:173] op_sel_hi:[1,0]
	v_pk_fma_f32 v[124:125], v[130:131], v[124:125], v[64:65]
	v_pk_fma_f32 v[126:127], v[132:133], v[126:127], v[66:67]
	s_nop 0
	s_nop 0
	v_cvt_pk_bf16_f32 v124, v124, v125
	s_nop 0
	s_nop 0
	s_nop 0
	v_cvt_pk_bf16_f32 v125, v126, v127
	v_add_co_u32_e32 v126, vcc, s24, v164
	v_pk_mul_f32 v[120:121], v[120:121], v[172:173] op_sel_hi:[1,0]
	s_nop 0
	v_addc_co_u32_e32 v127, vcc, 0, v165, vcc
	v_pk_fma_f32 v[120:121], v[134:135], v[120:121], v[68:69]
	global_store_dwordx2 v[126:127], v[124:125], off
	s_nop 0
	v_pk_mul_f32 v[122:123], v[122:123], v[172:173] op_sel_hi:[1,0]
	s_nop 0
	v_pk_fma_f32 v[122:123], v[136:137], v[122:123], v[70:71]
	v_cvt_pk_bf16_f32 v120, v120, v121
	v_bfe_u32 v121, v122, 16, 1
	v_add3_u32 v121, v122, v121, s65
	v_bfe_u32 v122, v123, 16, 1
	v_lshrrev_b32_e32 v121, 16, v121
	v_add3_u32 v122, v123, v122, s65
	v_pk_mul_f32 v[116:117], v[116:117], v[172:173] op_sel_hi:[1,0]
	v_and_or_b32 v121, v122, s61, v121
	v_pk_fma_f32 v[116:117], v[138:139], v[116:117], v[72:73]
	global_store_dwordx2 v[126:127], v[120:121], off offset:512
	v_pk_mul_f32 v[118:119], v[118:119], v[172:173] op_sel_hi:[1,0]
	v_pk_fma_f32 v[118:119], v[140:141], v[118:119], v[74:75]
	v_cvt_pk_bf16_f32 v116, v116, v117
	v_bfe_u32 v117, v118, 16, 1
	v_add3_u32 v117, v118, v117, s65
	v_bfe_u32 v118, v119, 16, 1
	v_lshrrev_b32_e32 v117, 16, v117
	v_add3_u32 v118, v119, v118, s65
	v_pk_mul_f32 v[112:113], v[112:113], v[172:173] op_sel_hi:[1,0]
	v_and_or_b32 v117, v118, s61, v117
	v_pk_fma_f32 v[112:113], v[142:143], v[112:113], v[76:77]
	global_store_dwordx2 v[126:127], v[116:117], off offset:1024
	v_pk_mul_f32 v[114:115], v[114:115], v[172:173] op_sel_hi:[1,0]
	v_pk_fma_f32 v[114:115], v[144:145], v[114:115], v[78:79]
	v_cvt_pk_bf16_f32 v112, v112, v113
	v_bfe_u32 v113, v114, 16, 1
	v_add3_u32 v113, v114, v113, s65
	v_bfe_u32 v114, v115, 16, 1
	v_lshrrev_b32_e32 v113, 16, v113
	v_add3_u32 v114, v115, v114, s65
	v_pk_mul_f32 v[108:109], v[108:109], v[172:173] op_sel_hi:[1,0]
	v_and_or_b32 v113, v114, s61, v113
	v_pk_fma_f32 v[108:109], v[146:147], v[108:109], v[80:81]
	global_store_dwordx2 v[126:127], v[112:113], off offset:1536
	v_pk_mul_f32 v[110:111], v[110:111], v[172:173] op_sel_hi:[1,0]
	v_pk_fma_f32 v[110:111], v[148:149], v[110:111], v[82:83]
	v_cvt_pk_bf16_f32 v108, v108, v109
	v_bfe_u32 v109, v110, 16, 1
	v_add3_u32 v109, v110, v109, s65
	v_bfe_u32 v110, v111, 16, 1
	v_lshrrev_b32_e32 v109, 16, v109
	v_add3_u32 v110, v111, v110, s65
	v_pk_mul_f32 v[104:105], v[104:105], v[172:173] op_sel_hi:[1,0]
	v_and_or_b32 v109, v110, s61, v109
	v_pk_fma_f32 v[104:105], v[150:151], v[104:105], v[84:85]
	global_store_dwordx2 v[126:127], v[108:109], off offset:2048
	v_pk_mul_f32 v[106:107], v[106:107], v[172:173] op_sel_hi:[1,0]
	v_pk_fma_f32 v[106:107], v[152:153], v[106:107], v[86:87]
	v_cvt_pk_bf16_f32 v104, v104, v105
	v_bfe_u32 v105, v106, 16, 1
	v_add3_u32 v105, v106, v105, s65
	v_bfe_u32 v106, v107, 16, 1
	v_lshrrev_b32_e32 v105, 16, v105
	v_add3_u32 v106, v107, v106, s65
	v_pk_mul_f32 v[100:101], v[100:101], v[172:173] op_sel_hi:[1,0]
	v_and_or_b32 v105, v106, s61, v105
	v_pk_fma_f32 v[100:101], v[154:155], v[100:101], v[88:89]
	global_store_dwordx2 v[126:127], v[104:105], off offset:2560
	v_pk_mul_f32 v[102:103], v[102:103], v[172:173] op_sel_hi:[1,0]
	v_pk_fma_f32 v[102:103], v[156:157], v[102:103], v[90:91]
	v_cvt_pk_bf16_f32 v100, v100, v101
	v_bfe_u32 v101, v102, 16, 1
	v_add3_u32 v101, v102, v101, s65
	v_bfe_u32 v102, v103, 16, 1
	v_lshrrev_b32_e32 v101, 16, v101
	v_add3_u32 v102, v103, v102, s65
	v_pk_mul_f32 v[96:97], v[96:97], v[172:173] op_sel_hi:[1,0]
	v_and_or_b32 v101, v102, s61, v101
	v_pk_fma_f32 v[96:97], v[158:159], v[96:97], v[92:93]
	global_store_dwordx2 v[126:127], v[100:101], off offset:3072
	v_pk_mul_f32 v[98:99], v[98:99], v[172:173] op_sel_hi:[1,0]
	v_pk_fma_f32 v[98:99], v[160:161], v[98:99], v[94:95]
	v_cvt_pk_bf16_f32 v96, v96, v97
	v_bfe_u32 v97, v98, 16, 1
	v_add3_u32 v97, v98, v97, s65
	v_bfe_u32 v98, v99, 16, 1
	v_lshrrev_b32_e32 v97, 16, v97
	v_add3_u32 v98, v99, v98, s65
	v_and_or_b32 v97, v98, s61, v97
	global_store_dwordx2 v[126:127], v[96:97], off offset:3584
	s_branch .LBB0_1205

.LBB0_1217:
	v_lshl_add_u64 v[108:109], s[0:1], 0, v[178:179]
	s_add_i32 s10, s24, 0xffffe000
	v_add_co_u32_e32 v0, vcc, 0x4b400000, v108
	s_ashr_i32 s10, s10, 12
	s_nop 0
	v_addc_co_u32_e32 v1, vcc, 0, v109, vcc
	s_add_i32 s10, s10, 1
	global_load_dwordx2 v[64:65], v[0:1], off
	global_load_dwordx2 v[66:67], v[0:1], off offset:512
	global_load_dwordx2 v[68:69], v[0:1], off offset:1024
	global_load_dwordx2 v[70:71], v[0:1], off offset:1536
	global_load_dwordx2 v[72:73], v[0:1], off offset:2048
	global_load_dwordx2 v[74:75], v[0:1], off offset:2560
	global_load_dwordx2 v[76:77], v[0:1], off offset:3072
	global_load_dwordx2 v[78:79], v[0:1], off offset:3584
	v_lshl_add_u64 v[0:1], s[2:3], 0, v[178:179]
	s_cmpk_gt_i32 s24, 0x1fff
	v_add_co_u32_e32 v0, vcc, 0x31200000, v0
	s_cselect_b32 s12, s10, 0
	s_nop 0
	v_addc_co_u32_e32 v1, vcc, 0, v1, vcc
	global_load_dwordx2 v[116:117], v[0:1], off
	global_load_dwordx2 v[118:119], v[0:1], off offset:512
	global_load_dwordx2 v[120:121], v[0:1], off offset:1024
	global_load_dwordx2 v[122:123], v[0:1], off offset:1536
	global_load_dwordx2 v[124:125], v[0:1], off offset:2048
	global_load_dwordx2 v[126:127], v[0:1], off offset:2560
	global_load_dwordx2 v[128:129], v[0:1], off offset:3072
	global_load_dwordx2 v[130:131], v[0:1], off offset:3584
	v_mad_i64_i32 v[0:1], s[10:11], s12, v224, v[100:101]
	s_movk_i32 s10, 0x1000
	global_load_dwordx4 v[28:31], v[80:81], off
	global_load_dwordx4 v[56:59], v[80:81], off offset:1024
	global_load_dwordx4 v[60:63], v[0:1], off
	global_load_dwordx4 v[24:27], v[0:1], off offset:1024
	global_load_dwordx4 v[52:55], v[80:81], off offset:2048
	global_load_dwordx4 v[48:51], v[80:81], off offset:3072
	global_load_dwordx4 v[20:23], v[0:1], off offset:2048
	global_load_dwordx4 v[16:19], v[0:1], off offset:3072
	v_add_co_u32_e32 v0, vcc, s10, v0
	s_nop 1
	v_addc_co_u32_e32 v1, vcc, 0, v1, vcc
	global_load_dwordx4 v[44:47], v[84:85], off
	global_load_dwordx4 v[40:43], v[86:87], off
	global_load_dwordx4 v[12:15], v[0:1], off
	global_load_dwordx4 v[8:11], v[0:1], off offset:1024
	global_load_dwordx4 v[36:39], v[88:89], off
	global_load_dwordx4 v[32:35], v[90:91], off
	global_load_dwordx4 v[4:7], v[0:1], off offset:2048
	s_nop 0
	global_load_dwordx4 v[0:3], v[0:1], off offset:3072
	s_waitcnt vmcnt(23)
	v_lshlrev_b32_e32 v136, 16, v116
	v_and_b32_e32 v137, 0xffff0000, v116
	v_lshlrev_b32_e32 v116, 16, v117
	v_and_b32_e32 v117, 0xffff0000, v117
	v_mul_f32_e32 v138, v117, v117
	s_waitcnt vmcnt(22)
	v_lshlrev_b32_e32 v141, 16, v119
	v_lshlrev_b32_e32 v140, 16, v118
	v_and_b32_e32 v119, 0xffff0000, v119
	v_and_b32_e32 v118, 0xffff0000, v118
	s_waitcnt vmcnt(20)
	v_lshlrev_b32_e32 v147, 16, v122
	v_mul_f32_e32 v146, v137, v137
	v_pk_fma_f32 v[138:139], v[116:117], v[116:117], v[138:139] op_sel_hi:[1,1,0]
	v_pk_mul_f32 v[142:143], v[118:119], v[118:119]
	v_pk_fma_f32 v[150:151], v[136:137], v[136:137], v[146:147] op_sel_hi:[1,1,0]
	v_pk_fma_f32 v[142:143], v[140:141], v[140:141], v[142:143]
	v_and_b32_e32 v149, 0xffff0000, v122
	v_mov_b32_e32 v146, v150
	v_mov_b32_e32 v152, v138
	v_mov_b32_e32 v153, v147
	v_mul_f32_e32 v135, v149, v149
	v_pk_add_f32 v[138:139], v[150:151], v[138:139]
	v_pk_mul_f32 v[150:151], v[146:147], v[152:153]
	v_pk_add_f32 v[142:143], v[142:143], v[142:143] op_sel:[0,1] op_sel_hi:[1,0]
	v_lshlrev_b32_e32 v144, 16, v120
	v_and_b32_e32 v145, 0xffff0000, v120
	v_lshlrev_b32_e32 v120, 16, v121
	v_and_b32_e32 v121, 0xffff0000, v121
	v_mov_b32_e32 v139, v151
	v_mov_b32_e32 v143, v135
	v_lshlrev_b32_e32 v122, 16, v123
	v_and_b32_e32 v123, 0xffff0000, v123
	v_pk_add_f32 v[138:139], v[138:139], v[142:143]
	v_mul_f32_e32 v142, v145, v145
	v_mul_f32_e32 v146, v121, v121
	v_mul_f32_e32 v148, v122, v122
	v_mul_f32_e32 v154, v123, v123
	v_pk_fma_f32 v[142:143], v[144:145], v[144:145], v[142:143] op_sel_hi:[1,1,0]
	v_pk_fma_f32 v[150:151], v[120:121], v[120:121], v[146:147] op_sel_hi:[1,1,0]
	v_mov_b32_e32 v143, v148
	v_mov_b32_e32 v151, v154
	v_pk_add_f32 v[142:143], v[142:143], v[150:151]
	s_waitcnt vmcnt(18)
	v_lshlrev_b32_e32 v153, 16, v127
	v_pk_add_f32 v[138:139], v[138:139], v[142:143]
	v_lshlrev_b32_e32 v143, 16, v125
	v_lshlrev_b32_e32 v142, 16, v124
	v_and_b32_e32 v125, 0xffff0000, v125
	v_and_b32_e32 v124, 0xffff0000, v124
	v_pk_mul_f32 v[150:151], v[124:125], v[124:125]
	v_lshlrev_b32_e32 v152, 16, v126
	v_pk_fma_f32 v[150:151], v[142:143], v[142:143], v[150:151]
	v_and_b32_e32 v127, 0xffff0000, v127
	v_pk_add_f32 v[150:151], v[150:151], v[150:151] op_sel:[0,1] op_sel_hi:[1,0]
	v_and_b32_e32 v126, 0xffff0000, v126
	s_waitcnt vmcnt(16)
	v_lshlrev_b32_e32 v159, 16, v130
	v_pk_add_f32 v[138:139], v[138:139], v[138:139] op_sel:[0,1] op_sel_hi:[1,0]
	v_pk_mul_f32 v[154:155], v[126:127], v[126:127]
	v_mov_b32_e32 v158, v138
	v_mov_b32_e32 v162, v150
	v_mov_b32_e32 v163, v159
	v_pk_fma_f32 v[154:155], v[152:153], v[152:153], v[154:155]
	v_and_b32_e32 v161, 0xffff0000, v130
	v_pk_add_f32 v[138:139], v[138:139], v[150:151]
	v_pk_mul_f32 v[150:151], v[158:159], v[162:163]
	v_and_b32_e32 v157, 0xffff0000, v128
	v_mul_f32_e32 v135, v161, v161
	v_mov_b32_e32 v139, v151
	v_pk_add_f32 v[150:151], v[154:155], v[154:155] op_sel:[0,1] op_sel_hi:[1,0]
	v_lshlrev_b32_e32 v156, 16, v128
	v_lshlrev_b32_e32 v128, 16, v129
	v_and_b32_e32 v129, 0xffff0000, v129
	v_mov_b32_e32 v151, v135
	v_mul_f32_e32 v146, v157, v157
	v_lshlrev_b32_e32 v130, 16, v131
	v_and_b32_e32 v131, 0xffff0000, v131
	v_pk_add_f32 v[138:139], v[138:139], v[150:151]
	v_pk_fma_f32 v[150:151], v[156:157], v[156:157], v[146:147] op_sel_hi:[1,1,0]
	v_mul_f32_e32 v146, v129, v129
	v_mul_f32_e32 v148, v130, v130
	v_mul_f32_e32 v160, v131, v131
	v_pk_fma_f32 v[154:155], v[128:129], v[128:129], v[146:147] op_sel_hi:[1,1,0]
	v_mov_b32_e32 v151, v148
	v_mov_b32_e32 v155, v160
	v_pk_add_f32 v[150:151], v[150:151], v[154:155]
	v_lshlrev_b32_e32 v132, 16, v64
	v_pk_add_f32 v[138:139], v[138:139], v[150:151]
	v_and_b32_e32 v133, 0xffff0000, v64
	v_add_f32_e32 v139, v138, v139
	v_lshlrev_b32_e32 v64, 16, v65
	v_and_b32_e32 v65, 0xffff0000, v65
	v_lshlrev_b32_e32 v134, 16, v66
	v_and_b32_e32 v135, 0xffff0000, v66
	s_waitcnt lgkmcnt(0)
	s_nop 1
	v_add_f32_dpp v146, v139, v139 quad_perm:[1,0,3,2] row_mask:0xf bank_mask:0xf
	s_nop 1
	v_add_f32_dpp v146, v146, v146 quad_perm:[2,3,0,1] row_mask:0xf bank_mask:0xf
	s_nop 1
	v_add_f32_dpp v146, v146, v146 row_half_mirror row_mask:0xf bank_mask:0xf
	s_nop 1
	v_add_f32_dpp v146, v146, v146 row_mirror row_mask:0xf bank_mask:0xf
	v_mov_b32_e32 v148, v146
	s_nop 1
	v_permlane16_swap_b32_e32 v146, v148
	v_add_f32_e32 v146, v146, v148
	v_mov_b32_e32 v148, v146
	s_nop 1
	v_permlane32_swap_b32_e32 v146, v148
	v_add_f32_e32 v146, v146, v148
	v_lshlrev_b32_e32 v66, 16, v67
	v_and_b32_e32 v67, 0xffff0000, v67
	v_lshlrev_b32_e32 v138, 16, v68
	v_and_b32_e32 v139, 0xffff0000, v68
	v_lshlrev_b32_e32 v68, 16, v69
	v_and_b32_e32 v69, 0xffff0000, v69
	v_lshlrev_b32_e32 v150, 16, v70
	v_and_b32_e32 v151, 0xffff0000, v70
	v_lshlrev_b32_e32 v70, 16, v71
	v_and_b32_e32 v71, 0xffff0000, v71
	v_lshlrev_b32_e32 v154, 16, v72
	v_and_b32_e32 v155, 0xffff0000, v72
	v_lshlrev_b32_e32 v72, 16, v73
	v_and_b32_e32 v73, 0xffff0000, v73
	v_lshlrev_b32_e32 v162, 16, v74
	v_and_b32_e32 v163, 0xffff0000, v74
	v_lshlrev_b32_e32 v74, 16, v75
	v_and_b32_e32 v75, 0xffff0000, v75
	v_lshlrev_b32_e32 v164, 16, v76
	v_and_b32_e32 v165, 0xffff0000, v76
	v_fmamk_f32 v146, v146, 0x3a000000, v252
	v_mul_f32_e32 v148, 0x4b800000, v146
	v_cmp_gt_f32_e32 vcc, s88, v146
	v_lshlrev_b32_e32 v76, 16, v77
	v_and_b32_e32 v77, 0xffff0000, v77
	v_cndmask_b32_e32 v146, v146, v148, vcc
	v_rsq_f32_e32 v146, v146
	v_mov_b32_e32 v160, v159
	v_lshlrev_b32_e32 v166, 16, v78
	v_and_b32_e32 v167, 0xffff0000, v78
	v_mul_f32_e32 v148, 0x45800000, v146
	v_cndmask_b32_e32 v146, v146, v148, vcc
	v_pk_mul_f32 v[136:137], v[146:147], v[136:137] op_sel_hi:[0,1]
	v_pk_mul_f32 v[116:117], v[146:147], v[116:117] op_sel_hi:[0,1]
	s_waitcnt vmcnt(15)
	v_pk_mul_f32 v[28:29], v[28:29], v[136:137]
	v_pk_mul_f32 v[30:31], v[30:31], v[116:117]
	s_waitcnt vmcnt(13)
	v_pk_fma_f32 v[28:29], v[60:61], v[28:29], v[132:133]
	v_mov_b32_e32 v60, v141
	v_mov_b32_e32 v141, v118
	v_pk_fma_f32 v[30:31], v[62:63], v[30:31], v[64:65]
	v_mov_b32_e32 v61, v119
	v_pk_mul_f32 v[62:63], v[146:147], v[140:141] op_sel_hi:[0,1]
	v_pk_mul_f32 v[60:61], v[146:147], v[60:61] op_sel_hi:[0,1]
	v_pk_mul_f32 v[56:57], v[56:57], v[62:63]
	v_pk_mul_f32 v[58:59], v[58:59], v[60:61]
	s_waitcnt vmcnt(12)
	v_pk_fma_f32 v[24:25], v[24:25], v[56:57], v[134:135]
	v_pk_mul_f32 v[56:57], v[146:147], v[120:121] op_sel_hi:[0,1]
	v_pk_fma_f32 v[26:27], v[26:27], v[58:59], v[66:67]
	v_pk_mul_f32 v[58:59], v[146:147], v[144:145] op_sel_hi:[0,1]
	s_waitcnt vmcnt(11)
	v_pk_mul_f32 v[54:55], v[54:55], v[56:57]
	v_mov_b32_e32 v148, v147
	v_pk_mul_f32 v[52:53], v[52:53], v[58:59]
	s_waitcnt vmcnt(9)
	v_pk_fma_f32 v[22:23], v[22:23], v[54:55], v[68:69]
	v_pk_mul_f32 v[54:55], v[148:149], v[146:147] op_sel_hi:[1,0]
	v_pk_fma_f32 v[20:21], v[20:21], v[52:53], v[138:139]
	v_pk_mul_f32 v[52:53], v[122:123], v[146:147] op_sel_hi:[1,0]
	v_pk_mul_f32 v[48:49], v[48:49], v[54:55]
	v_pk_mul_f32 v[50:51], v[50:51], v[52:53]
	s_waitcnt vmcnt(8)
	v_pk_fma_f32 v[16:17], v[16:17], v[48:49], v[150:151]
	v_mov_b32_e32 v48, v143
	v_mov_b32_e32 v143, v124
	v_pk_fma_f32 v[18:19], v[18:19], v[50:51], v[70:71]
	v_mov_b32_e32 v49, v125
	v_pk_mul_f32 v[50:51], v[146:147], v[142:143] op_sel_hi:[0,1]
	v_pk_mul_f32 v[48:49], v[146:147], v[48:49] op_sel_hi:[0,1]
	s_waitcnt vmcnt(7)
	v_pk_mul_f32 v[44:45], v[44:45], v[50:51]
	v_pk_mul_f32 v[46:47], v[46:47], v[48:49]
	s_waitcnt vmcnt(5)
	v_pk_fma_f32 v[12:13], v[12:13], v[44:45], v[154:155]
	v_mov_b32_e32 v44, v153
	v_mov_b32_e32 v45, v127
	v_mov_b32_e32 v153, v126
	v_pk_fma_f32 v[14:15], v[14:15], v[46:47], v[72:73]
	v_pk_mul_f32 v[44:45], v[146:147], v[44:45] op_sel_hi:[0,1]
	v_pk_mul_f32 v[46:47], v[146:147], v[152:153] op_sel_hi:[0,1]
	v_pk_mul_f32 v[40:41], v[40:41], v[46:47]
	v_pk_mul_f32 v[42:43], v[42:43], v[44:45]
	s_waitcnt vmcnt(4)
	v_pk_fma_f32 v[8:9], v[8:9], v[40:41], v[162:163]
	v_pk_fma_f32 v[10:11], v[10:11], v[42:43], v[74:75]
	v_pk_mul_f32 v[40:41], v[146:147], v[128:129] op_sel_hi:[0,1]
	v_pk_mul_f32 v[42:43], v[146:147], v[156:157] op_sel_hi:[0,1]
	s_waitcnt vmcnt(3)
	v_pk_mul_f32 v[36:37], v[36:37], v[42:43]
	v_pk_mul_f32 v[38:39], v[38:39], v[40:41]
	s_waitcnt vmcnt(1)
	v_pk_fma_f32 v[4:5], v[4:5], v[36:37], v[164:165]
	v_pk_fma_f32 v[6:7], v[6:7], v[38:39], v[76:77]
	v_pk_mul_f32 v[36:37], v[130:131], v[146:147] op_sel_hi:[1,0]
	v_pk_mul_f32 v[38:39], v[160:161], v[146:147] op_sel_hi:[1,0]
	v_lshlrev_b32_e32 v78, 16, v79
	v_and_b32_e32 v79, 0xffff0000, v79
	v_pk_mul_f32 v[32:33], v[32:33], v[38:39]
	v_pk_mul_f32 v[34:35], v[34:35], v[36:37]
	s_waitcnt vmcnt(0)
	v_pk_fma_f32 v[0:1], v[0:1], v[32:33], v[166:167]
	v_pk_fma_f32 v[2:3], v[2:3], v[34:35], v[78:79]
	s_mov_b64 s[10:11], -1
	s_and_b64 vcc, exec, s[4:5]
	s_cbranch_vccnz .LBB0_1220
	s_andn2_b64 vcc, exec, s[10:11]
	s_cbranch_vccz .LBB0_1221

.LBB0_1222:
	v_mad_i64_i32 v[32:33], s[10:11], s12, v224, v[102:103]
	v_mad_i64_i32 v[34:35], s[10:11], s12, v224, v[104:105]
	s_movk_i32 s10, 0x1000
	global_load_dwordx4 v[116:119], v[82:83], off
	global_load_dwordx4 v[120:123], v[82:83], off offset:1024
	global_load_dwordx4 v[124:127], v[32:33], off
	global_load_dwordx4 v[128:131], v[32:33], off offset:1024
	global_load_dwordx4 v[132:135], v[34:35], off
	global_load_dwordx4 v[136:139], v[34:35], off offset:1024
	global_load_dwordx4 v[140:143], v[82:83], off offset:2048
	global_load_dwordx4 v[144:147], v[82:83], off offset:3072
	global_load_dwordx4 v[148:151], v[32:33], off offset:2048
	global_load_dwordx4 v[152:155], v[32:33], off offset:3072
	global_load_dwordx4 v[156:159], v[34:35], off offset:2048
	global_load_dwordx4 v[160:163], v[34:35], off offset:3072
	v_add_co_u32_e32 v32, vcc, s10, v32
	s_nop 1
	v_addc_co_u32_e32 v33, vcc, 0, v33, vcc
	v_add_co_u32_e32 v34, vcc, s10, v34
	s_nop 1
	v_addc_co_u32_e32 v35, vcc, 0, v35, vcc
	global_load_dwordx4 v[72:75], v[92:93], off
	global_load_dwordx4 v[64:67], v[94:95], off
	global_load_dwordx4 v[76:79], v[32:33], off
	global_load_dwordx4 v[60:63], v[32:33], off offset:1024
	global_load_dwordx4 v[68:71], v[34:35], off
	global_load_dwordx4 v[56:59], v[34:35], off offset:1024
	global_load_dwordx4 v[48:51], v[96:97], off
	global_load_dwordx4 v[40:43], v[98:99], off
	global_load_dwordx4 v[52:55], v[32:33], off offset:2048
	global_load_dwordx4 v[36:39], v[32:33], off offset:3072
	global_load_dwordx4 v[44:47], v[34:35], off offset:2048
	s_nop 0
	global_load_dwordx4 v[32:35], v[34:35], off offset:3072
	v_mov_b32_e32 v166, v29
	v_mov_b32_e32 v167, v25
	v_mov_b32_e32 v164, v28
	v_mov_b32_e32 v165, v24
	v_pk_mul_f32 v[166:167], v[166:167], v[166:167]
	v_mov_b32_e32 v168, v31
	v_mov_b32_e32 v169, v27
	v_pk_fma_f32 v[164:165], v[164:165], v[164:165], v[166:167]
	v_mov_b32_e32 v166, v30
	v_mov_b32_e32 v167, v26
	v_pk_mul_f32 v[168:169], v[168:169], v[168:169]
	s_mov_b32 s10, 0x17800000
	v_pk_fma_f32 v[166:167], v[166:167], v[166:167], v[168:169]
	v_pk_mul_f32 v[168:169], v[20:21], v[20:21]
	v_pk_add_f32 v[164:165], v[164:165], v[166:167]
	v_pk_mul_f32 v[166:167], v[22:23], v[22:23]
	v_pk_add_f32 v[164:165], v[164:165], v[164:165] op_sel_hi:[0,1]
	v_pk_mov_b32 v[170:171], v[168:169], v[166:167] op_sel:[1,0]
	v_mov_b32_e32 v169, v167
	v_mul_f32_e32 v164, v16, v16
	v_pk_add_f32 v[166:167], v[170:171], v[168:169]
	v_pk_fma_f32 v[168:169], v[16:17], v[16:17], v[164:165] op_sel_hi:[1,1,0]
	v_mul_f32_e32 v164, v18, v18
	v_pk_add_f32 v[166:167], v[166:167], v[166:167] op_sel_hi:[0,1]
	v_pk_fma_f32 v[170:171], v[18:19], v[18:19], v[164:165] op_sel_hi:[1,1,0]
	v_mul_f32_e32 v168, v12, v12
	v_mul_f32_e32 v170, v13, v13
	v_mul_f32_e32 v166, v14, v14
	v_mul_f32_e32 v164, v15, v15
	v_pk_add_f32 v[168:169], v[168:169], v[170:171]
	v_pk_add_f32 v[164:165], v[166:167], v[164:165]
	v_pk_mul_f32 v[166:167], v[10:11], v[10:11]
	v_pk_add_f32 v[164:165], v[168:169], v[164:165]
	v_pk_mul_f32 v[168:169], v[8:9], v[8:9]
	v_pk_add_f32 v[164:165], v[164:165], v[164:165] op_sel_hi:[0,1]
	v_pk_mov_b32 v[170:171], v[168:169], v[166:167] op_sel:[1,0]
	v_mov_b32_e32 v169, v167
	v_mul_f32_e32 v164, v4, v4
	v_pk_add_f32 v[166:167], v[170:171], v[168:169]
	v_pk_fma_f32 v[168:169], v[4:5], v[4:5], v[164:165] op_sel_hi:[1,1,0]
	v_mul_f32_e32 v164, v6, v6
	v_pk_add_f32 v[166:167], v[166:167], v[166:167] op_sel_hi:[0,1]
	v_pk_fma_f32 v[170:171], v[6:7], v[6:7], v[164:165] op_sel_hi:[1,1,0]
	v_mul_f32_e32 v168, v0, v0
	v_mul_f32_e32 v170, v1, v1
	v_mul_f32_e32 v166, v2, v2
	v_mul_f32_e32 v164, v3, v3
	v_pk_add_f32 v[168:169], v[168:169], v[170:171]
	v_pk_add_f32 v[164:165], v[166:167], v[164:165]
	s_nop 0
	v_pk_add_f32 v[164:165], v[168:169], v[164:165]
	s_nop 0
	v_add_f32_e32 v164, v164, v165
	s_waitcnt lgkmcnt(0)
	s_nop 1
	v_add_f32_dpp v164, v164, v164 quad_perm:[1,0,3,2] row_mask:0xf bank_mask:0xf
	s_nop 1
	v_add_f32_dpp v164, v164, v164 quad_perm:[2,3,0,1] row_mask:0xf bank_mask:0xf
	s_nop 1
	v_add_f32_dpp v164, v164, v164 row_half_mirror row_mask:0xf bank_mask:0xf
	s_nop 1
	v_add_f32_dpp v164, v164, v164 row_mirror row_mask:0xf bank_mask:0xf
	v_mov_b32_e32 v165, v164
	s_nop 1
	v_permlane16_swap_b32_e32 v164, v165
	v_add_f32_e32 v164, v164, v165
	v_mov_b32_e32 v165, v164
	s_nop 1
	v_permlane32_swap_b32_e32 v164, v165
	v_add_f32_e32 v164, v164, v165
	v_fmamk_f32 v164, v164, 0x3a000000, v252
	v_mul_f32_e32 v165, 0x4b800000, v164
	v_cmp_gt_f32_e32 vcc, s88, v164
	s_nop 1
	v_cndmask_b32_e32 v164, v164, v165, vcc
	v_rsq_f32_e32 v164, v164
	s_nop 0
	v_mul_f32_e32 v165, 0x45800000, v164
	v_cndmask_b32_e32 v164, v164, v165, vcc
	v_pk_mul_f32 v[30:31], v[30:31], v[164:165] op_sel_hi:[1,0]
	v_pk_mul_f32 v[28:29], v[28:29], v[164:165] op_sel_hi:[1,0]
	s_waitcnt vmcnt(23)
	v_pk_mul_f32 v[30:31], v[118:119], v[30:31]
	v_pk_mul_f32 v[28:29], v[116:117], v[28:29]
	s_waitcnt vmcnt(21)
	v_pk_add_f32 v[118:119], v[124:125], 1.0 op_sel_hi:[1,0]
	v_pk_add_f32 v[116:117], v[126:127], 1.0 op_sel_hi:[1,0]
	s_waitcnt vmcnt(19)
	v_pk_fma_f32 v[28:29], v[118:119], v[28:29], v[132:133]
	v_pk_fma_f32 v[30:31], v[116:117], v[30:31], v[134:135]
	v_cvt_pk_bf16_f32 v28, v28, v29
	s_nop 0
	s_nop 0
	s_nop 0
	v_cvt_pk_bf16_f32 v29, v30, v31
	v_add_co_u32_e32 v30, vcc, s10, v108
	v_pk_mul_f32 v[24:25], v[24:25], v[164:165] op_sel_hi:[1,0]
	s_nop 0
	v_addc_co_u32_e32 v31, vcc, 0, v109, vcc
	v_pk_mul_f32 v[26:27], v[26:27], v[164:165] op_sel_hi:[1,0]
	v_pk_mul_f32 v[24:25], v[120:121], v[24:25]
	v_pk_add_f32 v[108:109], v[128:129], 1.0 op_sel_hi:[1,0]
	global_store_dwordx2 v[30:31], v[28:29], off
	v_pk_mul_f32 v[26:27], v[122:123], v[26:27]
	v_pk_add_f32 v[28:29], v[130:131], 1.0 op_sel_hi:[1,0]
	s_waitcnt vmcnt(19)
	v_pk_fma_f32 v[24:25], v[108:109], v[24:25], v[136:137]
	v_pk_fma_f32 v[26:27], v[28:29], v[26:27], v[138:139]
	v_cvt_pk_bf16_f32 v24, v24, v25
	v_pk_mul_f32 v[20:21], v[20:21], v[164:165] op_sel_hi:[1,0]
	v_cvt_pk_bf16_f32 v25, v26, v27
	v_pk_mul_f32 v[22:23], v[22:23], v[164:165] op_sel_hi:[1,0]
	s_waitcnt vmcnt(18)
	v_pk_mul_f32 v[20:21], v[140:141], v[20:21]
	s_waitcnt vmcnt(16)
	v_pk_add_f32 v[26:27], v[148:149], 1.0 op_sel_hi:[1,0]
	global_store_dwordx2 v[30:31], v[24:25], off offset:512
	v_pk_mul_f32 v[22:23], v[142:143], v[22:23]
	v_pk_add_f32 v[24:25], v[150:151], 1.0 op_sel_hi:[1,0]
	s_waitcnt vmcnt(15)
	v_pk_fma_f32 v[20:21], v[26:27], v[20:21], v[156:157]
	v_pk_fma_f32 v[22:23], v[24:25], v[22:23], v[158:159]
	v_cvt_pk_bf16_f32 v20, v20, v21
	v_pk_mul_f32 v[16:17], v[16:17], v[164:165] op_sel_hi:[1,0]
	v_cvt_pk_bf16_f32 v21, v22, v23
	v_pk_mul_f32 v[18:19], v[18:19], v[164:165] op_sel_hi:[1,0]
	v_pk_mul_f32 v[16:17], v[144:145], v[16:17]
	v_pk_add_f32 v[22:23], v[152:153], 1.0 op_sel_hi:[1,0]
	global_store_dwordx2 v[30:31], v[20:21], off offset:1024
	v_pk_mul_f32 v[18:19], v[146:147], v[18:19]
	v_pk_add_f32 v[20:21], v[154:155], 1.0 op_sel_hi:[1,0]
	s_waitcnt vmcnt(15)
	v_pk_fma_f32 v[16:17], v[22:23], v[16:17], v[160:161]
	v_pk_fma_f32 v[18:19], v[20:21], v[18:19], v[162:163]
	v_cvt_pk_bf16_f32 v16, v16, v17
	v_pk_mul_f32 v[12:13], v[12:13], v[164:165] op_sel_hi:[1,0]
	v_cvt_pk_bf16_f32 v17, v18, v19
	v_pk_mul_f32 v[14:15], v[14:15], v[164:165] op_sel_hi:[1,0]
	s_waitcnt vmcnt(14)
	v_pk_mul_f32 v[12:13], v[72:73], v[12:13]
	s_waitcnt vmcnt(12)
	v_pk_add_f32 v[18:19], v[76:77], 1.0 op_sel_hi:[1,0]
	global_store_dwordx2 v[30:31], v[16:17], off offset:1536
	v_pk_mul_f32 v[14:15], v[74:75], v[14:15]
	v_pk_add_f32 v[16:17], v[78:79], 1.0 op_sel_hi:[1,0]
	s_waitcnt vmcnt(11)
	v_pk_fma_f32 v[12:13], v[18:19], v[12:13], v[68:69]
	v_pk_fma_f32 v[14:15], v[16:17], v[14:15], v[70:71]
	v_cvt_pk_bf16_f32 v12, v12, v13
	v_pk_mul_f32 v[8:9], v[8:9], v[164:165] op_sel_hi:[1,0]
	v_cvt_pk_bf16_f32 v13, v14, v15
	v_pk_mul_f32 v[10:11], v[10:11], v[164:165] op_sel_hi:[1,0]
	v_pk_mul_f32 v[8:9], v[64:65], v[8:9]
	v_pk_add_f32 v[14:15], v[60:61], 1.0 op_sel_hi:[1,0]
	global_store_dwordx2 v[30:31], v[12:13], off offset:2048
	v_pk_mul_f32 v[10:11], v[66:67], v[10:11]
	v_pk_add_f32 v[12:13], v[62:63], 1.0 op_sel_hi:[1,0]
	s_waitcnt vmcnt(11)
	v_pk_fma_f32 v[8:9], v[14:15], v[8:9], v[56:57]
	v_pk_fma_f32 v[10:11], v[12:13], v[10:11], v[58:59]
	v_cvt_pk_bf16_f32 v8, v8, v9
	v_pk_mul_f32 v[4:5], v[4:5], v[164:165] op_sel_hi:[1,0]
	v_cvt_pk_bf16_f32 v9, v10, v11
	v_pk_mul_f32 v[6:7], v[6:7], v[164:165] op_sel_hi:[1,0]
	s_waitcnt vmcnt(10)
	v_pk_mul_f32 v[4:5], v[48:49], v[4:5]
	s_waitcnt vmcnt(8)
	v_pk_add_f32 v[10:11], v[52:53], 1.0 op_sel_hi:[1,0]
	global_store_dwordx2 v[30:31], v[8:9], off offset:2560
	v_pk_mul_f32 v[6:7], v[50:51], v[6:7]
	v_pk_add_f32 v[8:9], v[54:55], 1.0 op_sel_hi:[1,0]
	s_waitcnt vmcnt(7)
	v_pk_fma_f32 v[4:5], v[10:11], v[4:5], v[44:45]
	v_pk_fma_f32 v[6:7], v[8:9], v[6:7], v[46:47]
	v_cvt_pk_bf16_f32 v4, v4, v5
	v_pk_mul_f32 v[0:1], v[0:1], v[164:165] op_sel_hi:[1,0]
	v_cvt_pk_bf16_f32 v5, v6, v7
	v_pk_mul_f32 v[2:3], v[2:3], v[164:165] op_sel_hi:[1,0]
	v_pk_mul_f32 v[0:1], v[40:41], v[0:1]
	v_pk_add_f32 v[6:7], v[36:37], 1.0 op_sel_hi:[1,0]
	global_store_dwordx2 v[30:31], v[4:5], off offset:3072
	v_pk_mul_f32 v[2:3], v[42:43], v[2:3]
	v_pk_add_f32 v[4:5], v[38:39], 1.0 op_sel_hi:[1,0]
	s_waitcnt vmcnt(7)
	v_pk_fma_f32 v[0:1], v[6:7], v[0:1], v[32:33]
	v_pk_fma_f32 v[2:3], v[4:5], v[2:3], v[34:35]
	v_cvt_pk_bf16_f32 v0, v0, v1
	v_bfe_u32 v1, v2, 16, 1
	v_add3_u32 v1, v2, v1, s65
	v_bfe_u32 v2, v3, 16, 1
	v_lshrrev_b32_e32 v1, 16, v1
	v_add3_u32 v2, v3, v2, s65
	v_and_or_b32 v1, v2, s61, v1
	global_store_dwordx2 v[30:31], v[0:1], off offset:3584
	s_branch .LBB0_1216
